# mid-burst s_setprio 0/1 toggles removed from the four GEMM K-loops (24 sites)
# baseline (speedup 1.0000x reference)
.LBB0_161:
	s_ashr_i32 s79, s78, 31
	s_lshl_b64 s[70:71], s[78:79], 19
	s_add_u32 s80, s34, s70
	s_addc_u32 s81, s35, s71
	s_and_b64 s[70:71], s[2:3], exec
	s_cselect_b32 s79, s81, s87
	s_cselect_b32 vcc_lo, s80, s86
	s_ashr_i32 s13, s12, 31
	s_lshl_b64 s[70:71], s[12:13], 19
	s_add_u32 s82, s4, s70
	s_addc_u32 s83, s5, s71
	s_and_b64 s[70:71], s[2:3], exec
	s_cselect_b32 s13, s83, s89
	s_cselect_b32 vcc_hi, s82, s88
	s_add_u32 s86, s86, 0x40080
	s_addc_u32 s87, s87, 0
	s_add_u32 s70, s88, 0x100
	s_addc_u32 s71, s89, 0
	s_mov_b32 s72, -2
	ds_read_b128 v[144:147], v151
	ds_read_b128 v[154:157], v151 offset:1024
	ds_read_b128 v[158:161], v151 offset:2048
	ds_read_b128 v[162:165], v151 offset:3072
	ds_read_b128 v[170:173], v152
	ds_read_b128 v[174:177], v152 offset:1024
	ds_read_b128 v[178:181], v152 offset:2048
	ds_read_b128 v[182:185], v152 offset:3072
	s_add_u32 s0, s86, 0xfffc0080
	s_addc_u32 s1, s87, -1
	s_cmp_eq_u32 s72, 12
	s_cselect_b32 s91, s79, s1
	s_cselect_b32 s90, vcc_lo, s0
	s_cselect_b32 s89, s13, s71
	s_cselect_b32 s88, vcc_hi, s70
	v_lshl_add_u64 v[166:167], s[86:87], 0, v[136:137]
	s_add_i32 m0, s85, 0xc000
	ds_read_b128 v[194:197], v153
	ds_read_b128 v[198:201], v153 offset:1024
	ds_read_b128 v[202:205], v153 offset:2048
	ds_read_b128 v[206:209], v153 offset:3072
	ds_read_b128 v[210:213], v153 offset:4096
	ds_read_b128 v[214:217], v153 offset:5120
	ds_read_b128 v[218:221], v153 offset:6144
	ds_read_b128 v[222:225], v153 offset:7168
	global_load_lds_dwordx4 v[166:167], off
	v_lshl_add_u64 v[166:167], s[86:87], 0, v[138:139]
	s_add_i32 m0, s85, 0xe000
	s_nop 0
	global_load_lds_dwordx4 v[166:167], off
	s_waitcnt vmcnt(8)
	s_waitcnt lgkmcnt(0)
	s_barrier
	s_setprio 1
	s_waitcnt lgkmcnt(0)
	v_mfma_f32_16x16x32_bf16 v[124:127], v[144:147], v[194:197], 0
	v_mfma_f32_16x16x32_bf16 v[120:123], v[158:161], v[194:197], 0
	v_mfma_f32_16x16x32_bf16 v[116:119], v[144:147], v[202:205], 0
	v_mfma_f32_16x16x32_bf16 v[108:111], v[158:161], v[202:205], 0
	v_mfma_f32_16x16x32_bf16 v[100:103], v[144:147], v[210:213], 0
	v_mfma_f32_16x16x32_bf16 v[92:95], v[158:161], v[210:213], 0
	v_mfma_f32_16x16x32_bf16 v[84:87], v[144:147], v[218:221], 0
	v_mfma_f32_16x16x32_bf16 v[76:79], v[158:161], v[218:221], 0
	v_mfma_f32_16x16x32_bf16 v[124:127], v[154:157], v[198:201], v[124:127]
	v_mfma_f32_16x16x32_bf16 v[120:123], v[162:165], v[198:201], v[120:123]
	v_mfma_f32_16x16x32_bf16 v[116:119], v[154:157], v[206:209], v[116:119]
	v_mfma_f32_16x16x32_bf16 v[108:111], v[162:165], v[206:209], v[108:111]
	v_mfma_f32_16x16x32_bf16 v[100:103], v[154:157], v[214:217], v[100:103]
	v_mfma_f32_16x16x32_bf16 v[92:95], v[162:165], v[214:217], v[92:95]
	v_mfma_f32_16x16x32_bf16 v[84:87], v[154:157], v[222:225], v[84:87]
	v_mfma_f32_16x16x32_bf16 v[76:79], v[162:165], v[222:225], v[76:79]
	v_mfma_f32_16x16x32_bf16 v[112:115], v[170:173], v[194:197], 0
	v_mfma_f32_16x16x32_bf16 v[104:107], v[178:181], v[194:197], 0
	v_mfma_f32_16x16x32_bf16 v[96:99], v[170:173], v[202:205], 0
	v_mfma_f32_16x16x32_bf16 v[88:91], v[178:181], v[202:205], 0
	v_mfma_f32_16x16x32_bf16 v[80:83], v[170:173], v[210:213], 0
	v_mfma_f32_16x16x32_bf16 v[72:75], v[178:181], v[210:213], 0
	v_mfma_f32_16x16x32_bf16 v[68:71], v[170:173], v[218:221], 0
	v_mfma_f32_16x16x32_bf16 v[64:67], v[178:181], v[218:221], 0
	v_mfma_f32_16x16x32_bf16 v[112:115], v[174:177], v[198:201], v[112:115]
	v_mfma_f32_16x16x32_bf16 v[104:107], v[182:185], v[198:201], v[104:107]
	v_mfma_f32_16x16x32_bf16 v[96:99], v[174:177], v[206:209], v[96:99]
	v_mfma_f32_16x16x32_bf16 v[88:91], v[182:185], v[206:209], v[88:91]
	v_mfma_f32_16x16x32_bf16 v[80:83], v[174:177], v[214:217], v[80:83]
	v_mfma_f32_16x16x32_bf16 v[72:75], v[182:185], v[214:217], v[72:75]
	v_mfma_f32_16x16x32_bf16 v[68:71], v[174:177], v[222:225], v[68:71]
	v_mfma_f32_16x16x32_bf16 v[64:67], v[182:185], v[222:225], v[64:67]
	s_setprio 0
	s_barrier
	s_add_i32 s0, s18, s75
	v_lshl_add_u64 v[166:167], s[88:89], 0, v[130:131]
	s_mov_b32 m0, s0
	ds_read_b128 v[194:197], v153 offset:16384
	ds_read_b128 v[198:201], v153 offset:17408
	ds_read_b128 v[202:205], v153 offset:18432
	ds_read_b128 v[206:209], v153 offset:19456
	ds_read_b128 v[210:213], v153 offset:20480
	ds_read_b128 v[214:217], v153 offset:21504
	ds_read_b128 v[218:221], v153 offset:22528
	ds_read_b128 v[222:225], v153 offset:23552
	global_load_lds_dwordx4 v[166:167], off
	s_add_i32 m0, s0, 0x2000
	s_add_u32 s0, s88, 0x40000
	v_lshl_add_u64 v[168:169], s[88:89], 0, v[134:135]
	s_addc_u32 s1, s89, 0
	s_add_i32 s73, s19, s75
	global_load_lds_dwordx4 v[168:169], off
	v_lshl_add_u64 v[186:187], s[0:1], 0, v[130:131]
	s_mov_b32 m0, s73
	v_lshl_add_u64 v[190:191], s[90:91], 0, v[132:133]
	global_load_lds_dwordx4 v[186:187], off
	v_lshl_add_u64 v[186:187], s[0:1], 0, v[134:135]
	s_add_i32 m0, s73, 0x2000
	s_nop 0
	global_load_lds_dwordx4 v[186:187], off
	v_lshl_add_u64 v[186:187], s[90:91], 0, v[128:129]
	s_mov_b32 m0, s85
	s_nop 0
	global_load_lds_dwordx4 v[186:187], off
	s_mov_b32 m0, s76
	s_nop 0
	global_load_lds_dwordx4 v[190:191], off
	s_waitcnt vmcnt(8)
	s_waitcnt lgkmcnt(0)
	s_barrier
	s_setprio 1
	s_waitcnt lgkmcnt(0)
	v_mfma_f32_16x16x32_bf16 v[60:63], v[144:147], v[194:197], 0
	v_mfma_f32_16x16x32_bf16 v[56:59], v[158:161], v[194:197], 0
	v_mfma_f32_16x16x32_bf16 v[52:55], v[144:147], v[202:205], 0
	v_mfma_f32_16x16x32_bf16 v[44:47], v[158:161], v[202:205], 0
	v_mfma_f32_16x16x32_bf16 v[36:39], v[144:147], v[210:213], 0
	v_mfma_f32_16x16x32_bf16 v[28:31], v[158:161], v[210:213], 0
	v_mfma_f32_16x16x32_bf16 v[20:23], v[144:147], v[218:221], 0
	v_mfma_f32_16x16x32_bf16 v[12:15], v[158:161], v[218:221], 0
	v_mfma_f32_16x16x32_bf16 v[60:63], v[154:157], v[198:201], v[60:63]
	v_mfma_f32_16x16x32_bf16 v[56:59], v[162:165], v[198:201], v[56:59]
	v_mfma_f32_16x16x32_bf16 v[52:55], v[154:157], v[206:209], v[52:55]
	v_mfma_f32_16x16x32_bf16 v[44:47], v[162:165], v[206:209], v[44:47]
	v_mfma_f32_16x16x32_bf16 v[36:39], v[154:157], v[214:217], v[36:39]
	v_mfma_f32_16x16x32_bf16 v[28:31], v[162:165], v[214:217], v[28:31]
	v_mfma_f32_16x16x32_bf16 v[20:23], v[154:157], v[222:225], v[20:23]
	v_mfma_f32_16x16x32_bf16 v[12:15], v[162:165], v[222:225], v[12:15]
	v_mfma_f32_16x16x32_bf16 v[48:51], v[170:173], v[194:197], 0
	v_mfma_f32_16x16x32_bf16 v[40:43], v[178:181], v[194:197], 0
	v_mfma_f32_16x16x32_bf16 v[32:35], v[170:173], v[202:205], 0
	v_mfma_f32_16x16x32_bf16 v[24:27], v[178:181], v[202:205], 0
	v_mfma_f32_16x16x32_bf16 v[16:19], v[170:173], v[210:213], 0
	v_mfma_f32_16x16x32_bf16 v[8:11], v[178:181], v[210:213], 0
	v_mfma_f32_16x16x32_bf16 v[4:7], v[170:173], v[218:221], 0
	v_mfma_f32_16x16x32_bf16 v[0:3], v[178:181], v[218:221], 0
	v_mfma_f32_16x16x32_bf16 v[48:51], v[174:177], v[198:201], v[48:51]
	v_mfma_f32_16x16x32_bf16 v[40:43], v[182:185], v[198:201], v[40:43]
	v_mfma_f32_16x16x32_bf16 v[32:35], v[174:177], v[206:209], v[32:35]
	v_mfma_f32_16x16x32_bf16 v[24:27], v[182:185], v[206:209], v[24:27]
	v_mfma_f32_16x16x32_bf16 v[16:19], v[174:177], v[214:217], v[16:19]
	v_mfma_f32_16x16x32_bf16 v[8:11], v[182:185], v[214:217], v[8:11]
	v_mfma_f32_16x16x32_bf16 v[4:7], v[174:177], v[222:225], v[4:7]
	v_mfma_f32_16x16x32_bf16 v[0:3], v[182:185], v[222:225], v[0:3]
	s_setprio 0
	s_barrier
	s_branch .Lpeelp1_mid
.LBB0_162:
	ds_read_b128 v[144:147], v151
	ds_read_b128 v[154:157], v151 offset:1024
	ds_read_b128 v[158:161], v151 offset:2048
	ds_read_b128 v[162:165], v151 offset:3072
	ds_read_b128 v[170:173], v152
	ds_read_b128 v[174:177], v152 offset:1024
	ds_read_b128 v[178:181], v152 offset:2048
	ds_read_b128 v[182:185], v152 offset:3072
	s_add_u32 s0, s86, 0xfffc0080
	s_addc_u32 s1, s87, -1
	s_cmp_eq_u32 s72, 12
	s_cselect_b32 s91, s79, s1
	s_cselect_b32 s90, vcc_lo, s0
	s_cselect_b32 s89, s13, s71
	s_cselect_b32 s88, vcc_hi, s70
	v_lshl_add_u64 v[166:167], s[86:87], 0, v[136:137]
	s_add_i32 m0, s85, 0xc000
	ds_read_b128 v[194:197], v153
	ds_read_b128 v[198:201], v153 offset:1024
	ds_read_b128 v[202:205], v153 offset:2048
	ds_read_b128 v[206:209], v153 offset:3072
	ds_read_b128 v[210:213], v153 offset:4096
	ds_read_b128 v[214:217], v153 offset:5120
	ds_read_b128 v[218:221], v153 offset:6144
	ds_read_b128 v[222:225], v153 offset:7168
	global_load_lds_dwordx4 v[166:167], off
	v_lshl_add_u64 v[166:167], s[86:87], 0, v[138:139]
	s_add_i32 m0, s85, 0xe000
	s_nop 0
	global_load_lds_dwordx4 v[166:167], off
	s_waitcnt vmcnt(8)
	s_waitcnt lgkmcnt(0)
	s_barrier
	s_setprio 1
	s_waitcnt lgkmcnt(0)
	v_mfma_f32_16x16x32_bf16 v[124:127], v[144:147], v[194:197], v[124:127]
	v_mfma_f32_16x16x32_bf16 v[120:123], v[158:161], v[194:197], v[120:123]
	v_mfma_f32_16x16x32_bf16 v[116:119], v[144:147], v[202:205], v[116:119]
	v_mfma_f32_16x16x32_bf16 v[108:111], v[158:161], v[202:205], v[108:111]
	v_mfma_f32_16x16x32_bf16 v[100:103], v[144:147], v[210:213], v[100:103]
	v_mfma_f32_16x16x32_bf16 v[92:95], v[158:161], v[210:213], v[92:95]
	v_mfma_f32_16x16x32_bf16 v[84:87], v[144:147], v[218:221], v[84:87]
	v_mfma_f32_16x16x32_bf16 v[76:79], v[158:161], v[218:221], v[76:79]
	v_mfma_f32_16x16x32_bf16 v[124:127], v[154:157], v[198:201], v[124:127]
	v_mfma_f32_16x16x32_bf16 v[120:123], v[162:165], v[198:201], v[120:123]
	v_mfma_f32_16x16x32_bf16 v[116:119], v[154:157], v[206:209], v[116:119]
	v_mfma_f32_16x16x32_bf16 v[108:111], v[162:165], v[206:209], v[108:111]
	v_mfma_f32_16x16x32_bf16 v[100:103], v[154:157], v[214:217], v[100:103]
	v_mfma_f32_16x16x32_bf16 v[92:95], v[162:165], v[214:217], v[92:95]
	v_mfma_f32_16x16x32_bf16 v[84:87], v[154:157], v[222:225], v[84:87]
	v_mfma_f32_16x16x32_bf16 v[76:79], v[162:165], v[222:225], v[76:79]
	v_mfma_f32_16x16x32_bf16 v[112:115], v[170:173], v[194:197], v[112:115]
	v_mfma_f32_16x16x32_bf16 v[104:107], v[178:181], v[194:197], v[104:107]
	v_mfma_f32_16x16x32_bf16 v[96:99], v[170:173], v[202:205], v[96:99]
	v_mfma_f32_16x16x32_bf16 v[88:91], v[178:181], v[202:205], v[88:91]
	v_mfma_f32_16x16x32_bf16 v[80:83], v[170:173], v[210:213], v[80:83]
	v_mfma_f32_16x16x32_bf16 v[72:75], v[178:181], v[210:213], v[72:75]
	v_mfma_f32_16x16x32_bf16 v[68:71], v[170:173], v[218:221], v[68:71]
	v_mfma_f32_16x16x32_bf16 v[64:67], v[178:181], v[218:221], v[64:67]
	v_mfma_f32_16x16x32_bf16 v[112:115], v[174:177], v[198:201], v[112:115]
	v_mfma_f32_16x16x32_bf16 v[104:107], v[182:185], v[198:201], v[104:107]
	v_mfma_f32_16x16x32_bf16 v[96:99], v[174:177], v[206:209], v[96:99]
	v_mfma_f32_16x16x32_bf16 v[88:91], v[182:185], v[206:209], v[88:91]
	v_mfma_f32_16x16x32_bf16 v[80:83], v[174:177], v[214:217], v[80:83]
	v_mfma_f32_16x16x32_bf16 v[72:75], v[182:185], v[214:217], v[72:75]
	v_mfma_f32_16x16x32_bf16 v[68:71], v[174:177], v[222:225], v[68:71]
	v_mfma_f32_16x16x32_bf16 v[64:67], v[182:185], v[222:225], v[64:67]
	s_setprio 0
	s_barrier
	s_add_i32 s0, s18, s75
	v_lshl_add_u64 v[166:167], s[88:89], 0, v[130:131]
	s_mov_b32 m0, s0
	ds_read_b128 v[194:197], v153 offset:16384
	ds_read_b128 v[198:201], v153 offset:17408
	ds_read_b128 v[202:205], v153 offset:18432
	ds_read_b128 v[206:209], v153 offset:19456
	ds_read_b128 v[210:213], v153 offset:20480
	ds_read_b128 v[214:217], v153 offset:21504
	ds_read_b128 v[218:221], v153 offset:22528
	ds_read_b128 v[222:225], v153 offset:23552
	global_load_lds_dwordx4 v[166:167], off
	s_add_i32 m0, s0, 0x2000
	s_add_u32 s0, s88, 0x40000
	v_lshl_add_u64 v[168:169], s[88:89], 0, v[134:135]
	s_addc_u32 s1, s89, 0
	s_add_i32 s73, s19, s75
	global_load_lds_dwordx4 v[168:169], off
	v_lshl_add_u64 v[186:187], s[0:1], 0, v[130:131]
	s_mov_b32 m0, s73
	v_lshl_add_u64 v[190:191], s[90:91], 0, v[132:133]
	global_load_lds_dwordx4 v[186:187], off
	v_lshl_add_u64 v[186:187], s[0:1], 0, v[134:135]
	s_add_i32 m0, s73, 0x2000
	s_nop 0
	global_load_lds_dwordx4 v[186:187], off
	v_lshl_add_u64 v[186:187], s[90:91], 0, v[128:129]
	s_mov_b32 m0, s85
	s_nop 0
	global_load_lds_dwordx4 v[186:187], off
	s_mov_b32 m0, s76
	s_nop 0
	global_load_lds_dwordx4 v[190:191], off
	s_waitcnt vmcnt(8)
	s_waitcnt lgkmcnt(0)
	s_barrier
	s_setprio 1
	s_waitcnt lgkmcnt(0)
	v_mfma_f32_16x16x32_bf16 v[60:63], v[144:147], v[194:197], v[60:63]
	v_mfma_f32_16x16x32_bf16 v[56:59], v[158:161], v[194:197], v[56:59]
	v_mfma_f32_16x16x32_bf16 v[52:55], v[144:147], v[202:205], v[52:55]
	v_mfma_f32_16x16x32_bf16 v[44:47], v[158:161], v[202:205], v[44:47]
	v_mfma_f32_16x16x32_bf16 v[36:39], v[144:147], v[210:213], v[36:39]
	v_mfma_f32_16x16x32_bf16 v[28:31], v[158:161], v[210:213], v[28:31]
	v_mfma_f32_16x16x32_bf16 v[20:23], v[144:147], v[218:221], v[20:23]
	v_mfma_f32_16x16x32_bf16 v[12:15], v[158:161], v[218:221], v[12:15]
	v_mfma_f32_16x16x32_bf16 v[60:63], v[154:157], v[198:201], v[60:63]
	v_mfma_f32_16x16x32_bf16 v[56:59], v[162:165], v[198:201], v[56:59]
	v_mfma_f32_16x16x32_bf16 v[52:55], v[154:157], v[206:209], v[52:55]
	v_mfma_f32_16x16x32_bf16 v[44:47], v[162:165], v[206:209], v[44:47]
	v_mfma_f32_16x16x32_bf16 v[36:39], v[154:157], v[214:217], v[36:39]
	v_mfma_f32_16x16x32_bf16 v[28:31], v[162:165], v[214:217], v[28:31]
	v_mfma_f32_16x16x32_bf16 v[20:23], v[154:157], v[222:225], v[20:23]
	v_mfma_f32_16x16x32_bf16 v[12:15], v[162:165], v[222:225], v[12:15]
	v_mfma_f32_16x16x32_bf16 v[48:51], v[170:173], v[194:197], v[48:51]
	v_mfma_f32_16x16x32_bf16 v[40:43], v[178:181], v[194:197], v[40:43]
	v_mfma_f32_16x16x32_bf16 v[32:35], v[170:173], v[202:205], v[32:35]
	v_mfma_f32_16x16x32_bf16 v[24:27], v[178:181], v[202:205], v[24:27]
	v_mfma_f32_16x16x32_bf16 v[16:19], v[170:173], v[210:213], v[16:19]
	v_mfma_f32_16x16x32_bf16 v[8:11], v[178:181], v[210:213], v[8:11]
	v_mfma_f32_16x16x32_bf16 v[4:7], v[170:173], v[218:221], v[4:7]
	v_mfma_f32_16x16x32_bf16 v[0:3], v[178:181], v[218:221], v[0:3]
	v_mfma_f32_16x16x32_bf16 v[48:51], v[174:177], v[198:201], v[48:51]
	v_mfma_f32_16x16x32_bf16 v[40:43], v[182:185], v[198:201], v[40:43]
	v_mfma_f32_16x16x32_bf16 v[32:35], v[174:177], v[206:209], v[32:35]
	v_mfma_f32_16x16x32_bf16 v[24:27], v[182:185], v[206:209], v[24:27]
	v_mfma_f32_16x16x32_bf16 v[16:19], v[174:177], v[214:217], v[16:19]
	v_mfma_f32_16x16x32_bf16 v[8:11], v[182:185], v[214:217], v[8:11]
	v_mfma_f32_16x16x32_bf16 v[4:7], v[174:177], v[222:225], v[4:7]
	v_mfma_f32_16x16x32_bf16 v[0:3], v[182:185], v[222:225], v[0:3]
	s_setprio 0
	s_barrier
.Lpeelp1_mid:
	s_add_i32 s73, 0, 0x18000
	s_add_i32 s16, 0, 0x1c000
	v_add_u32_e32 v162, s73, v149
	v_add_u32_e32 v182, s16, v149
	ds_read_b128 v[144:147], v162
	ds_read_b128 v[154:157], v162 offset:1024
	ds_read_b128 v[158:161], v162 offset:2048
	ds_read_b128 v[162:165], v162 offset:3072
	ds_read_b128 v[170:173], v182
	ds_read_b128 v[174:177], v182 offset:1024
	ds_read_b128 v[178:181], v182 offset:2048
	ds_read_b128 v[182:185], v182 offset:3072
	s_add_u32 s0, s90, 0x40000
	s_addc_u32 s1, s91, 0
	s_mov_b32 m0, s77
	v_lshl_add_u64 v[192:193], s[0:1], 0, v[128:129]
	ds_read_b128 v[194:197], v153 offset:32768
	ds_read_b128 v[198:201], v153 offset:33792
	ds_read_b128 v[202:205], v153 offset:34816
	ds_read_b128 v[206:209], v153 offset:35840
	ds_read_b128 v[210:213], v153 offset:36864
	ds_read_b128 v[214:217], v153 offset:37888
	ds_read_b128 v[218:221], v153 offset:38912
	ds_read_b128 v[222:225], v153 offset:39936
	global_load_lds_dwordx4 v[192:193], off
	v_lshl_add_u64 v[192:193], s[0:1], 0, v[132:133]
	s_mov_b32 m0, s68
	s_nop 0
	global_load_lds_dwordx4 v[192:193], off
	s_waitcnt vmcnt(8)
	s_waitcnt lgkmcnt(0)
	s_barrier
	s_setprio 1
	s_waitcnt lgkmcnt(0)
	v_mfma_f32_16x16x32_bf16 v[124:127], v[144:147], v[194:197], v[124:127]
	v_mfma_f32_16x16x32_bf16 v[120:123], v[158:161], v[194:197], v[120:123]
	v_mfma_f32_16x16x32_bf16 v[116:119], v[144:147], v[202:205], v[116:119]
	v_mfma_f32_16x16x32_bf16 v[108:111], v[158:161], v[202:205], v[108:111]
	v_mfma_f32_16x16x32_bf16 v[100:103], v[144:147], v[210:213], v[100:103]
	v_mfma_f32_16x16x32_bf16 v[92:95], v[158:161], v[210:213], v[92:95]
	v_mfma_f32_16x16x32_bf16 v[84:87], v[144:147], v[218:221], v[84:87]
	v_mfma_f32_16x16x32_bf16 v[76:79], v[158:161], v[218:221], v[76:79]
	v_mfma_f32_16x16x32_bf16 v[124:127], v[154:157], v[198:201], v[124:127]
	v_mfma_f32_16x16x32_bf16 v[120:123], v[162:165], v[198:201], v[120:123]
	v_mfma_f32_16x16x32_bf16 v[116:119], v[154:157], v[206:209], v[116:119]
	v_mfma_f32_16x16x32_bf16 v[108:111], v[162:165], v[206:209], v[108:111]
	v_mfma_f32_16x16x32_bf16 v[100:103], v[154:157], v[214:217], v[100:103]
	v_mfma_f32_16x16x32_bf16 v[92:95], v[162:165], v[214:217], v[92:95]
	v_mfma_f32_16x16x32_bf16 v[84:87], v[154:157], v[222:225], v[84:87]
	v_mfma_f32_16x16x32_bf16 v[76:79], v[162:165], v[222:225], v[76:79]
	v_mfma_f32_16x16x32_bf16 v[112:115], v[170:173], v[194:197], v[112:115]
	v_mfma_f32_16x16x32_bf16 v[104:107], v[178:181], v[194:197], v[104:107]
	v_mfma_f32_16x16x32_bf16 v[96:99], v[170:173], v[202:205], v[96:99]
	v_mfma_f32_16x16x32_bf16 v[88:91], v[178:181], v[202:205], v[88:91]
	v_mfma_f32_16x16x32_bf16 v[80:83], v[170:173], v[210:213], v[80:83]
	v_mfma_f32_16x16x32_bf16 v[72:75], v[178:181], v[210:213], v[72:75]
	v_mfma_f32_16x16x32_bf16 v[68:71], v[170:173], v[218:221], v[68:71]
	v_mfma_f32_16x16x32_bf16 v[64:67], v[178:181], v[218:221], v[64:67]
	v_mfma_f32_16x16x32_bf16 v[112:115], v[174:177], v[198:201], v[112:115]
	v_mfma_f32_16x16x32_bf16 v[104:107], v[182:185], v[198:201], v[104:107]
	v_mfma_f32_16x16x32_bf16 v[96:99], v[174:177], v[206:209], v[96:99]
	v_mfma_f32_16x16x32_bf16 v[88:91], v[182:185], v[206:209], v[88:91]
	v_mfma_f32_16x16x32_bf16 v[80:83], v[174:177], v[214:217], v[80:83]
	v_mfma_f32_16x16x32_bf16 v[72:75], v[182:185], v[214:217], v[72:75]
	v_mfma_f32_16x16x32_bf16 v[68:71], v[174:177], v[222:225], v[68:71]
	v_mfma_f32_16x16x32_bf16 v[64:67], v[182:185], v[222:225], v[64:67]
	s_setprio 0
	s_barrier
	s_add_i32 s0, s73, s75
	v_lshl_add_u64 v[166:167], v[166:167], 0, s[8:9]
	s_mov_b32 m0, s0
	ds_read_b128 v[194:197], v153 offset:49152
	ds_read_b128 v[198:201], v153 offset:50176
	ds_read_b128 v[202:205], v153 offset:51200
	ds_read_b128 v[206:209], v153 offset:52224
	ds_read_b128 v[210:213], v153 offset:53248
	ds_read_b128 v[214:217], v153 offset:54272
	ds_read_b128 v[218:221], v153 offset:55296
	ds_read_b128 v[222:225], v153 offset:56320
	global_load_lds_dwordx4 v[166:167], off
	s_add_i32 m0, s0, 0x2000
	s_add_u32 s0, s88, 0x40080
	v_lshl_add_u64 v[166:167], v[168:169], 0, s[8:9]
	s_addc_u32 s1, s89, 0
	s_add_i32 s16, s16, s75
	global_load_lds_dwordx4 v[166:167], off
	v_lshl_add_u64 v[166:167], s[0:1], 0, v[130:131]
	s_mov_b32 m0, s16
	s_nop 0
	global_load_lds_dwordx4 v[166:167], off
	v_lshl_add_u64 v[166:167], s[0:1], 0, v[134:135]
	s_add_i32 m0, s16, 0x2000
	s_nop 0
	global_load_lds_dwordx4 v[166:167], off
	v_lshl_add_u64 v[166:167], v[186:187], 0, s[8:9]
	s_mov_b32 m0, s15
	s_nop 0
	global_load_lds_dwordx4 v[166:167], off
	v_lshl_add_u64 v[166:167], v[190:191], 0, s[8:9]
	s_mov_b32 m0, s94
	s_nop 0
	global_load_lds_dwordx4 v[166:167], off
	s_waitcnt vmcnt(8)
	s_waitcnt lgkmcnt(0)
	s_barrier
	s_setprio 1
	s_waitcnt lgkmcnt(0)
	v_mfma_f32_16x16x32_bf16 v[60:63], v[144:147], v[194:197], v[60:63]
	v_mfma_f32_16x16x32_bf16 v[56:59], v[158:161], v[194:197], v[56:59]
	v_mfma_f32_16x16x32_bf16 v[52:55], v[144:147], v[202:205], v[52:55]
	v_mfma_f32_16x16x32_bf16 v[44:47], v[158:161], v[202:205], v[44:47]
	v_mfma_f32_16x16x32_bf16 v[36:39], v[144:147], v[210:213], v[36:39]
	v_mfma_f32_16x16x32_bf16 v[28:31], v[158:161], v[210:213], v[28:31]
	v_mfma_f32_16x16x32_bf16 v[20:23], v[144:147], v[218:221], v[20:23]
	v_mfma_f32_16x16x32_bf16 v[12:15], v[158:161], v[218:221], v[12:15]
	v_mfma_f32_16x16x32_bf16 v[60:63], v[154:157], v[198:201], v[60:63]
	v_mfma_f32_16x16x32_bf16 v[56:59], v[162:165], v[198:201], v[56:59]
	v_mfma_f32_16x16x32_bf16 v[52:55], v[154:157], v[206:209], v[52:55]
	v_mfma_f32_16x16x32_bf16 v[44:47], v[162:165], v[206:209], v[44:47]
	v_mfma_f32_16x16x32_bf16 v[36:39], v[154:157], v[214:217], v[36:39]
	v_mfma_f32_16x16x32_bf16 v[28:31], v[162:165], v[214:217], v[28:31]
	v_mfma_f32_16x16x32_bf16 v[20:23], v[154:157], v[222:225], v[20:23]
	v_mfma_f32_16x16x32_bf16 v[12:15], v[162:165], v[222:225], v[12:15]
	v_mfma_f32_16x16x32_bf16 v[48:51], v[170:173], v[194:197], v[48:51]
	v_mfma_f32_16x16x32_bf16 v[40:43], v[178:181], v[194:197], v[40:43]
	v_mfma_f32_16x16x32_bf16 v[32:35], v[170:173], v[202:205], v[32:35]
	v_mfma_f32_16x16x32_bf16 v[24:27], v[178:181], v[202:205], v[24:27]
	v_mfma_f32_16x16x32_bf16 v[16:19], v[170:173], v[210:213], v[16:19]
	v_mfma_f32_16x16x32_bf16 v[8:11], v[178:181], v[210:213], v[8:11]
	v_mfma_f32_16x16x32_bf16 v[4:7], v[170:173], v[218:221], v[4:7]
	v_mfma_f32_16x16x32_bf16 v[0:3], v[178:181], v[218:221], v[0:3]
	v_mfma_f32_16x16x32_bf16 v[48:51], v[174:177], v[198:201], v[48:51]
	v_mfma_f32_16x16x32_bf16 v[40:43], v[182:185], v[198:201], v[40:43]
	v_mfma_f32_16x16x32_bf16 v[32:35], v[174:177], v[206:209], v[32:35]
	v_mfma_f32_16x16x32_bf16 v[24:27], v[182:185], v[206:209], v[24:27]
	v_mfma_f32_16x16x32_bf16 v[16:19], v[174:177], v[214:217], v[16:19]
	v_mfma_f32_16x16x32_bf16 v[8:11], v[182:185], v[214:217], v[8:11]
	v_mfma_f32_16x16x32_bf16 v[4:7], v[174:177], v[222:225], v[4:7]
	v_mfma_f32_16x16x32_bf16 v[0:3], v[182:185], v[222:225], v[0:3]
	s_setprio 0
	s_barrier
	s_add_i32 s72, s72, 2
	s_add_u32 s86, s86, 0x100
	s_addc_u32 s87, s87, 0
	s_add_u32 s70, s70, 0x100
	s_addc_u32 s71, s71, 0
	s_cmp_gt_u32 s72, 13
	s_cbranch_scc0 .LBB0_162
	s_and_b64 vcc, exec, s[10:11]
	s_cbranch_vccz .LBB0_165
	s_barrier

.LBB0_599:
	s_ashr_i32 s25, s24, 31
	s_lshl_b64 s[18:19], s[24:25], 19
	s_add_u32 s38, s34, s18
	s_addc_u32 s39, s35, s19
	s_and_b64 s[18:19], s[2:3], exec
	s_cselect_b32 s18, s39, s47
	s_cselect_b32 s19, s38, s46
	s_ashr_i32 s23, s22, 31
	s_lshl_b64 s[40:41], s[22:23], 19
	s_add_u32 s40, s74, s40
	s_addc_u32 s41, s75, s41
	s_and_b64 s[50:51], s[2:3], exec
	s_cselect_b32 s23, s41, s49
	s_cselect_b32 s25, s40, s48
	v_lshl_add_u32 v0, s24, 8, v148
	s_add_u32 s46, s46, 0x40080
	s_waitcnt lgkmcnt(0)
	v_ashrrev_i32_e32 v1, 31, v0
	s_addc_u32 s47, s47, 0
	v_lshl_add_u64 v[144:145], v[0:1], 2, s[6:7]
	s_add_u32 s33, s48, 0x100
	s_addc_u32 s43, s49, 0
	s_mov_b32 s63, -2
	s_waitcnt vmcnt(2)
	v_mov_b32_e32 v163, v154
	v_mov_b32_e32 v162, v155
	v_mov_b32_e32 v161, v164
	v_mov_b32_e32 v160, v165
	v_mov_b32_e32 v159, v166
	v_mov_b32_e32 v158, v167
	v_mov_b32_e32 v157, v168
	v_mov_b32_e32 v156, v169
	s_mov_b64 s[48:49], 0
	v_add_u32_e32 v146, s61, v149
	ds_read_b128 v[170:173], v146
	ds_read_b128 v[174:177], v146 offset:1024
	ds_read_b128 v[178:181], v146 offset:2048
	ds_read_b128 v[182:185], v146 offset:3072
	v_add_u32_e32 v146, s62, v149
	ds_read_b128 v[190:193], v146
	ds_read_b128 v[194:197], v146 offset:1024
	ds_read_b128 v[198:201], v146 offset:2048
	ds_read_b128 v[202:205], v146 offset:3072
	s_add_u32 s16, s46, 0xfffc0080
	s_addc_u32 s50, s47, -1
	s_and_b64 s[48:49], s[48:49], exec
	s_cselect_b32 s51, s18, s50
	s_cselect_b32 s50, s19, s16
	s_cselect_b32 s49, s23, s43
	s_cselect_b32 s48, s25, s33
	v_lshl_add_u64 v[146:147], s[46:47], 0, v[136:137]
	s_add_i32 m0, s45, 0xc000
	ds_read_b128 v[206:209], v151
	ds_read_b128 v[210:213], v151 offset:1024
	ds_read_b128 v[214:217], v151 offset:2048
	ds_read_b128 v[218:221], v151 offset:3072
	ds_read_b128 v[222:225], v151 offset:4096
	ds_read_b128 v[226:229], v151 offset:5120
	ds_read_b128 v[230:233], v151 offset:6144
	ds_read_b128 v[234:237], v151 offset:7168
	global_load_lds_dwordx4 v[146:147], off
	v_lshl_add_u64 v[146:147], s[46:47], 0, v[138:139]
	s_add_i32 m0, s45, 0xe000
	s_nop 0
	global_load_lds_dwordx4 v[146:147], off
	s_waitcnt vmcnt(8)
	s_waitcnt lgkmcnt(0)
	s_barrier
	s_setprio 1
	s_waitcnt lgkmcnt(0)
	v_mfma_f32_16x16x32_bf16 v[124:127], v[170:173], v[206:209], 0
	v_mfma_f32_16x16x32_bf16 v[120:123], v[178:181], v[206:209], 0
	v_mfma_f32_16x16x32_bf16 v[108:111], v[170:173], v[214:217], 0
	v_mfma_f32_16x16x32_bf16 v[104:107], v[178:181], v[214:217], 0
	v_mfma_f32_16x16x32_bf16 v[92:95], v[170:173], v[222:225], 0
	v_mfma_f32_16x16x32_bf16 v[88:91], v[178:181], v[222:225], 0
	v_mfma_f32_16x16x32_bf16 v[76:79], v[170:173], v[230:233], 0
	v_mfma_f32_16x16x32_bf16 v[72:75], v[178:181], v[230:233], 0
	v_mfma_f32_16x16x32_bf16 v[124:127], v[174:177], v[210:213], v[124:127]
	v_mfma_f32_16x16x32_bf16 v[120:123], v[182:185], v[210:213], v[120:123]
	v_mfma_f32_16x16x32_bf16 v[108:111], v[174:177], v[218:221], v[108:111]
	v_mfma_f32_16x16x32_bf16 v[104:107], v[182:185], v[218:221], v[104:107]
	v_mfma_f32_16x16x32_bf16 v[92:95], v[174:177], v[226:229], v[92:95]
	v_mfma_f32_16x16x32_bf16 v[88:91], v[182:185], v[226:229], v[88:91]
	v_mfma_f32_16x16x32_bf16 v[76:79], v[174:177], v[234:237], v[76:79]
	v_mfma_f32_16x16x32_bf16 v[72:75], v[182:185], v[234:237], v[72:75]
	v_mfma_f32_16x16x32_bf16 v[116:119], v[190:193], v[206:209], 0
	v_mfma_f32_16x16x32_bf16 v[112:115], v[198:201], v[206:209], 0
	v_mfma_f32_16x16x32_bf16 v[100:103], v[190:193], v[214:217], 0
	v_mfma_f32_16x16x32_bf16 v[96:99], v[198:201], v[214:217], 0
	v_mfma_f32_16x16x32_bf16 v[84:87], v[190:193], v[222:225], 0
	v_mfma_f32_16x16x32_bf16 v[80:83], v[198:201], v[222:225], 0
	v_mfma_f32_16x16x32_bf16 v[68:71], v[190:193], v[230:233], 0
	v_mfma_f32_16x16x32_bf16 v[64:67], v[198:201], v[230:233], 0
	v_mfma_f32_16x16x32_bf16 v[116:119], v[194:197], v[210:213], v[116:119]
	v_mfma_f32_16x16x32_bf16 v[112:115], v[202:205], v[210:213], v[112:115]
	v_mfma_f32_16x16x32_bf16 v[100:103], v[194:197], v[218:221], v[100:103]
	v_mfma_f32_16x16x32_bf16 v[96:99], v[202:205], v[218:221], v[96:99]
	v_mfma_f32_16x16x32_bf16 v[84:87], v[194:197], v[226:229], v[84:87]
	v_mfma_f32_16x16x32_bf16 v[80:83], v[202:205], v[226:229], v[80:83]
	v_mfma_f32_16x16x32_bf16 v[68:71], v[194:197], v[234:237], v[68:71]
	v_mfma_f32_16x16x32_bf16 v[64:67], v[202:205], v[234:237], v[64:67]
	s_setprio 0
	s_barrier
	s_add_i32 s16, s61, s52
	v_lshl_add_u64 v[146:147], s[48:49], 0, v[130:131]
	s_mov_b32 m0, s16
	ds_read_b128 v[206:209], v151 offset:16384
	ds_read_b128 v[210:213], v151 offset:17408
	ds_read_b128 v[214:217], v151 offset:18432
	ds_read_b128 v[218:221], v151 offset:19456
	ds_read_b128 v[222:225], v151 offset:20480
	ds_read_b128 v[226:229], v151 offset:21504
	ds_read_b128 v[230:233], v151 offset:22528
	ds_read_b128 v[234:237], v151 offset:23552
	global_load_lds_dwordx4 v[146:147], off
	s_add_i32 m0, s16, 0x2000
	s_add_u32 s64, s48, 0x40000
	v_lshl_add_u64 v[186:187], s[48:49], 0, v[134:135]
	s_addc_u32 s65, s49, 0
	s_add_i32 s16, s62, s52
	global_load_lds_dwordx4 v[186:187], off
	v_lshl_add_u64 v[238:239], s[64:65], 0, v[130:131]
	s_mov_b32 m0, s16
	v_lshl_add_u64 v[240:241], s[50:51], 0, v[132:133]
	global_load_lds_dwordx4 v[238:239], off
	v_lshl_add_u64 v[238:239], s[64:65], 0, v[134:135]
	s_add_i32 m0, s16, 0x2000
	s_nop 0
	global_load_lds_dwordx4 v[238:239], off
	v_lshl_add_u64 v[238:239], s[50:51], 0, v[128:129]
	s_mov_b32 m0, s45
	s_nop 0
	global_load_lds_dwordx4 v[238:239], off
	s_mov_b32 m0, s53
	s_nop 0
	global_load_lds_dwordx4 v[240:241], off
	s_waitcnt vmcnt(8)
	s_waitcnt lgkmcnt(0)
	s_barrier
	s_setprio 1
	s_waitcnt lgkmcnt(0)
	v_mfma_f32_16x16x32_bf16 v[60:63], v[170:173], v[206:209], 0
	v_mfma_f32_16x16x32_bf16 v[56:59], v[178:181], v[206:209], 0
	v_mfma_f32_16x16x32_bf16 v[44:47], v[170:173], v[214:217], 0
	v_mfma_f32_16x16x32_bf16 v[40:43], v[178:181], v[214:217], 0
	v_mfma_f32_16x16x32_bf16 v[28:31], v[170:173], v[222:225], 0
	v_mfma_f32_16x16x32_bf16 v[24:27], v[178:181], v[222:225], 0
	v_mfma_f32_16x16x32_bf16 v[12:15], v[170:173], v[230:233], 0
	v_mfma_f32_16x16x32_bf16 v[8:11], v[178:181], v[230:233], 0
	v_mfma_f32_16x16x32_bf16 v[60:63], v[174:177], v[210:213], v[60:63]
	v_mfma_f32_16x16x32_bf16 v[56:59], v[182:185], v[210:213], v[56:59]
	v_mfma_f32_16x16x32_bf16 v[44:47], v[174:177], v[218:221], v[44:47]
	v_mfma_f32_16x16x32_bf16 v[40:43], v[182:185], v[218:221], v[40:43]
	v_mfma_f32_16x16x32_bf16 v[28:31], v[174:177], v[226:229], v[28:31]
	v_mfma_f32_16x16x32_bf16 v[24:27], v[182:185], v[226:229], v[24:27]
	v_mfma_f32_16x16x32_bf16 v[12:15], v[174:177], v[234:237], v[12:15]
	v_mfma_f32_16x16x32_bf16 v[8:11], v[182:185], v[234:237], v[8:11]
	v_mfma_f32_16x16x32_bf16 v[52:55], v[190:193], v[206:209], 0
	v_mfma_f32_16x16x32_bf16 v[48:51], v[198:201], v[206:209], 0
	v_mfma_f32_16x16x32_bf16 v[36:39], v[190:193], v[214:217], 0
	v_mfma_f32_16x16x32_bf16 v[32:35], v[198:201], v[214:217], 0
	v_mfma_f32_16x16x32_bf16 v[20:23], v[190:193], v[222:225], 0
	v_mfma_f32_16x16x32_bf16 v[16:19], v[198:201], v[222:225], 0
	v_mfma_f32_16x16x32_bf16 v[4:7], v[190:193], v[230:233], 0
	v_mfma_f32_16x16x32_bf16 v[0:3], v[198:201], v[230:233], 0
	v_mfma_f32_16x16x32_bf16 v[52:55], v[194:197], v[210:213], v[52:55]
	v_mfma_f32_16x16x32_bf16 v[48:51], v[202:205], v[210:213], v[48:51]
	v_mfma_f32_16x16x32_bf16 v[36:39], v[194:197], v[218:221], v[36:39]
	v_mfma_f32_16x16x32_bf16 v[32:35], v[202:205], v[218:221], v[32:35]
	v_mfma_f32_16x16x32_bf16 v[20:23], v[194:197], v[226:229], v[20:23]
	v_mfma_f32_16x16x32_bf16 v[16:19], v[202:205], v[226:229], v[16:19]
	v_mfma_f32_16x16x32_bf16 v[4:7], v[194:197], v[234:237], v[4:7]
	v_mfma_f32_16x16x32_bf16 v[0:3], v[202:205], v[234:237], v[0:3]
	s_setprio 0
	s_barrier
	s_branch .Lpeelp5_mid
.LBB0_600:
	v_add_u32_e32 v146, s61, v149
	ds_read_b128 v[170:173], v146
	ds_read_b128 v[174:177], v146 offset:1024
	ds_read_b128 v[178:181], v146 offset:2048
	ds_read_b128 v[182:185], v146 offset:3072
	v_add_u32_e32 v146, s62, v149
	ds_read_b128 v[190:193], v146
	ds_read_b128 v[194:197], v146 offset:1024
	ds_read_b128 v[198:201], v146 offset:2048
	ds_read_b128 v[202:205], v146 offset:3072
	s_add_u32 s16, s46, 0xfffc0080
	s_addc_u32 s50, s47, -1
	s_and_b64 s[48:49], s[48:49], exec
	s_cselect_b32 s51, s18, s50
	s_cselect_b32 s50, s19, s16
	s_cselect_b32 s49, s23, s43
	s_cselect_b32 s48, s25, s33
	v_lshl_add_u64 v[146:147], s[46:47], 0, v[136:137]
	s_add_i32 m0, s45, 0xc000
	ds_read_b128 v[206:209], v151
	ds_read_b128 v[210:213], v151 offset:1024
	ds_read_b128 v[214:217], v151 offset:2048
	ds_read_b128 v[218:221], v151 offset:3072
	ds_read_b128 v[222:225], v151 offset:4096
	ds_read_b128 v[226:229], v151 offset:5120
	ds_read_b128 v[230:233], v151 offset:6144
	ds_read_b128 v[234:237], v151 offset:7168
	global_load_lds_dwordx4 v[146:147], off
	v_lshl_add_u64 v[146:147], s[46:47], 0, v[138:139]
	s_add_i32 m0, s45, 0xe000
	s_nop 0
	global_load_lds_dwordx4 v[146:147], off
	s_waitcnt vmcnt(8)
	s_waitcnt lgkmcnt(0)
	s_barrier
	s_setprio 1
	s_waitcnt lgkmcnt(0)
	v_mfma_f32_16x16x32_bf16 v[124:127], v[170:173], v[206:209], v[124:127]
	v_mfma_f32_16x16x32_bf16 v[120:123], v[178:181], v[206:209], v[120:123]
	v_mfma_f32_16x16x32_bf16 v[108:111], v[170:173], v[214:217], v[108:111]
	v_mfma_f32_16x16x32_bf16 v[104:107], v[178:181], v[214:217], v[104:107]
	v_mfma_f32_16x16x32_bf16 v[92:95], v[170:173], v[222:225], v[92:95]
	v_mfma_f32_16x16x32_bf16 v[88:91], v[178:181], v[222:225], v[88:91]
	v_mfma_f32_16x16x32_bf16 v[76:79], v[170:173], v[230:233], v[76:79]
	v_mfma_f32_16x16x32_bf16 v[72:75], v[178:181], v[230:233], v[72:75]
	v_mfma_f32_16x16x32_bf16 v[124:127], v[174:177], v[210:213], v[124:127]
	v_mfma_f32_16x16x32_bf16 v[120:123], v[182:185], v[210:213], v[120:123]
	v_mfma_f32_16x16x32_bf16 v[108:111], v[174:177], v[218:221], v[108:111]
	v_mfma_f32_16x16x32_bf16 v[104:107], v[182:185], v[218:221], v[104:107]
	v_mfma_f32_16x16x32_bf16 v[92:95], v[174:177], v[226:229], v[92:95]
	v_mfma_f32_16x16x32_bf16 v[88:91], v[182:185], v[226:229], v[88:91]
	v_mfma_f32_16x16x32_bf16 v[76:79], v[174:177], v[234:237], v[76:79]
	v_mfma_f32_16x16x32_bf16 v[72:75], v[182:185], v[234:237], v[72:75]
	v_mfma_f32_16x16x32_bf16 v[116:119], v[190:193], v[206:209], v[116:119]
	v_mfma_f32_16x16x32_bf16 v[112:115], v[198:201], v[206:209], v[112:115]
	v_mfma_f32_16x16x32_bf16 v[100:103], v[190:193], v[214:217], v[100:103]
	v_mfma_f32_16x16x32_bf16 v[96:99], v[198:201], v[214:217], v[96:99]
	v_mfma_f32_16x16x32_bf16 v[84:87], v[190:193], v[222:225], v[84:87]
	v_mfma_f32_16x16x32_bf16 v[80:83], v[198:201], v[222:225], v[80:83]
	v_mfma_f32_16x16x32_bf16 v[68:71], v[190:193], v[230:233], v[68:71]
	v_mfma_f32_16x16x32_bf16 v[64:67], v[198:201], v[230:233], v[64:67]
	v_mfma_f32_16x16x32_bf16 v[116:119], v[194:197], v[210:213], v[116:119]
	v_mfma_f32_16x16x32_bf16 v[112:115], v[202:205], v[210:213], v[112:115]
	v_mfma_f32_16x16x32_bf16 v[100:103], v[194:197], v[218:221], v[100:103]
	v_mfma_f32_16x16x32_bf16 v[96:99], v[202:205], v[218:221], v[96:99]
	v_mfma_f32_16x16x32_bf16 v[84:87], v[194:197], v[226:229], v[84:87]
	v_mfma_f32_16x16x32_bf16 v[80:83], v[202:205], v[226:229], v[80:83]
	v_mfma_f32_16x16x32_bf16 v[68:71], v[194:197], v[234:237], v[68:71]
	v_mfma_f32_16x16x32_bf16 v[64:67], v[202:205], v[234:237], v[64:67]
	s_setprio 0
	s_barrier
	s_add_i32 s16, s61, s52
	v_lshl_add_u64 v[146:147], s[48:49], 0, v[130:131]
	s_mov_b32 m0, s16
	ds_read_b128 v[206:209], v151 offset:16384
	ds_read_b128 v[210:213], v151 offset:17408
	ds_read_b128 v[214:217], v151 offset:18432
	ds_read_b128 v[218:221], v151 offset:19456
	ds_read_b128 v[222:225], v151 offset:20480
	ds_read_b128 v[226:229], v151 offset:21504
	ds_read_b128 v[230:233], v151 offset:22528
	ds_read_b128 v[234:237], v151 offset:23552
	global_load_lds_dwordx4 v[146:147], off
	s_add_i32 m0, s16, 0x2000
	s_add_u32 s64, s48, 0x40000
	v_lshl_add_u64 v[186:187], s[48:49], 0, v[134:135]
	s_addc_u32 s65, s49, 0
	s_add_i32 s16, s62, s52
	global_load_lds_dwordx4 v[186:187], off
	v_lshl_add_u64 v[238:239], s[64:65], 0, v[130:131]
	s_mov_b32 m0, s16
	v_lshl_add_u64 v[240:241], s[50:51], 0, v[132:133]
	global_load_lds_dwordx4 v[238:239], off
	v_lshl_add_u64 v[238:239], s[64:65], 0, v[134:135]
	s_add_i32 m0, s16, 0x2000
	s_nop 0
	global_load_lds_dwordx4 v[238:239], off
	v_lshl_add_u64 v[238:239], s[50:51], 0, v[128:129]
	s_mov_b32 m0, s45
	s_nop 0
	global_load_lds_dwordx4 v[238:239], off
	s_mov_b32 m0, s53
	s_nop 0
	global_load_lds_dwordx4 v[240:241], off
	s_waitcnt vmcnt(8)
	s_waitcnt lgkmcnt(0)
	s_barrier
	s_setprio 1
	s_waitcnt lgkmcnt(0)
	v_mfma_f32_16x16x32_bf16 v[60:63], v[170:173], v[206:209], v[60:63]
	v_mfma_f32_16x16x32_bf16 v[56:59], v[178:181], v[206:209], v[56:59]
	v_mfma_f32_16x16x32_bf16 v[44:47], v[170:173], v[214:217], v[44:47]
	v_mfma_f32_16x16x32_bf16 v[40:43], v[178:181], v[214:217], v[40:43]
	v_mfma_f32_16x16x32_bf16 v[28:31], v[170:173], v[222:225], v[28:31]
	v_mfma_f32_16x16x32_bf16 v[24:27], v[178:181], v[222:225], v[24:27]
	v_mfma_f32_16x16x32_bf16 v[12:15], v[170:173], v[230:233], v[12:15]
	v_mfma_f32_16x16x32_bf16 v[8:11], v[178:181], v[230:233], v[8:11]
	v_mfma_f32_16x16x32_bf16 v[60:63], v[174:177], v[210:213], v[60:63]
	v_mfma_f32_16x16x32_bf16 v[56:59], v[182:185], v[210:213], v[56:59]
	v_mfma_f32_16x16x32_bf16 v[44:47], v[174:177], v[218:221], v[44:47]
	v_mfma_f32_16x16x32_bf16 v[40:43], v[182:185], v[218:221], v[40:43]
	v_mfma_f32_16x16x32_bf16 v[28:31], v[174:177], v[226:229], v[28:31]
	v_mfma_f32_16x16x32_bf16 v[24:27], v[182:185], v[226:229], v[24:27]
	v_mfma_f32_16x16x32_bf16 v[12:15], v[174:177], v[234:237], v[12:15]
	v_mfma_f32_16x16x32_bf16 v[8:11], v[182:185], v[234:237], v[8:11]
	v_mfma_f32_16x16x32_bf16 v[52:55], v[190:193], v[206:209], v[52:55]
	v_mfma_f32_16x16x32_bf16 v[48:51], v[198:201], v[206:209], v[48:51]
	v_mfma_f32_16x16x32_bf16 v[36:39], v[190:193], v[214:217], v[36:39]
	v_mfma_f32_16x16x32_bf16 v[32:35], v[198:201], v[214:217], v[32:35]
	v_mfma_f32_16x16x32_bf16 v[20:23], v[190:193], v[222:225], v[20:23]
	v_mfma_f32_16x16x32_bf16 v[16:19], v[198:201], v[222:225], v[16:19]
	v_mfma_f32_16x16x32_bf16 v[4:7], v[190:193], v[230:233], v[4:7]
	v_mfma_f32_16x16x32_bf16 v[0:3], v[198:201], v[230:233], v[0:3]
	v_mfma_f32_16x16x32_bf16 v[52:55], v[194:197], v[210:213], v[52:55]
	v_mfma_f32_16x16x32_bf16 v[48:51], v[202:205], v[210:213], v[48:51]
	v_mfma_f32_16x16x32_bf16 v[36:39], v[194:197], v[218:221], v[36:39]
	v_mfma_f32_16x16x32_bf16 v[32:35], v[202:205], v[218:221], v[32:35]
	v_mfma_f32_16x16x32_bf16 v[20:23], v[194:197], v[226:229], v[20:23]
	v_mfma_f32_16x16x32_bf16 v[16:19], v[202:205], v[226:229], v[16:19]
	v_mfma_f32_16x16x32_bf16 v[4:7], v[194:197], v[234:237], v[4:7]
	v_mfma_f32_16x16x32_bf16 v[0:3], v[202:205], v[234:237], v[0:3]
	s_setprio 0
	s_barrier
.Lpeelp5_mid:
	s_add_i32 s16, 0, 0x18000
	s_add_i32 s64, 0, 0x1c000
	v_add_u32_e32 v182, s16, v149
	v_add_u32_e32 v188, s64, v149
	ds_read_b128 v[170:173], v182
	ds_read_b128 v[174:177], v182 offset:1024
	ds_read_b128 v[178:181], v182 offset:2048
	ds_read_b128 v[182:185], v182 offset:3072
	ds_read_b128 v[190:193], v188
	ds_read_b128 v[194:197], v188 offset:1024
	ds_read_b128 v[198:201], v188 offset:2048
	ds_read_b128 v[202:205], v188 offset:3072
	s_add_u32 s50, s50, 0x40000
	s_addc_u32 s51, s51, 0
	s_mov_b32 m0, s54
	v_lshl_add_u64 v[242:243], s[50:51], 0, v[128:129]
	ds_read_b128 v[206:209], v151 offset:32768
	ds_read_b128 v[210:213], v151 offset:33792
	ds_read_b128 v[214:217], v151 offset:34816
	ds_read_b128 v[218:221], v151 offset:35840
	ds_read_b128 v[222:225], v151 offset:36864
	ds_read_b128 v[226:229], v151 offset:37888
	ds_read_b128 v[230:233], v151 offset:38912
	ds_read_b128 v[234:237], v151 offset:39936
	global_load_lds_dwordx4 v[242:243], off
	v_lshl_add_u64 v[242:243], s[50:51], 0, v[132:133]
	s_mov_b32 m0, s55
	s_nop 0
	global_load_lds_dwordx4 v[242:243], off
	s_waitcnt vmcnt(8)
	s_waitcnt lgkmcnt(0)
	s_barrier
	s_setprio 1
	s_waitcnt lgkmcnt(0)
	v_mfma_f32_16x16x32_bf16 v[124:127], v[170:173], v[206:209], v[124:127]
	v_mfma_f32_16x16x32_bf16 v[120:123], v[178:181], v[206:209], v[120:123]
	v_mfma_f32_16x16x32_bf16 v[108:111], v[170:173], v[214:217], v[108:111]
	v_mfma_f32_16x16x32_bf16 v[104:107], v[178:181], v[214:217], v[104:107]
	v_mfma_f32_16x16x32_bf16 v[92:95], v[170:173], v[222:225], v[92:95]
	v_mfma_f32_16x16x32_bf16 v[88:91], v[178:181], v[222:225], v[88:91]
	v_mfma_f32_16x16x32_bf16 v[76:79], v[170:173], v[230:233], v[76:79]
	v_mfma_f32_16x16x32_bf16 v[72:75], v[178:181], v[230:233], v[72:75]
	v_mfma_f32_16x16x32_bf16 v[124:127], v[174:177], v[210:213], v[124:127]
	v_mfma_f32_16x16x32_bf16 v[120:123], v[182:185], v[210:213], v[120:123]
	v_mfma_f32_16x16x32_bf16 v[108:111], v[174:177], v[218:221], v[108:111]
	v_mfma_f32_16x16x32_bf16 v[104:107], v[182:185], v[218:221], v[104:107]
	v_mfma_f32_16x16x32_bf16 v[92:95], v[174:177], v[226:229], v[92:95]
	v_mfma_f32_16x16x32_bf16 v[88:91], v[182:185], v[226:229], v[88:91]
	v_mfma_f32_16x16x32_bf16 v[76:79], v[174:177], v[234:237], v[76:79]
	v_mfma_f32_16x16x32_bf16 v[72:75], v[182:185], v[234:237], v[72:75]
	v_mfma_f32_16x16x32_bf16 v[116:119], v[190:193], v[206:209], v[116:119]
	v_mfma_f32_16x16x32_bf16 v[112:115], v[198:201], v[206:209], v[112:115]
	v_mfma_f32_16x16x32_bf16 v[100:103], v[190:193], v[214:217], v[100:103]
	v_mfma_f32_16x16x32_bf16 v[96:99], v[198:201], v[214:217], v[96:99]
	v_mfma_f32_16x16x32_bf16 v[84:87], v[190:193], v[222:225], v[84:87]
	v_mfma_f32_16x16x32_bf16 v[80:83], v[198:201], v[222:225], v[80:83]
	v_mfma_f32_16x16x32_bf16 v[68:71], v[190:193], v[230:233], v[68:71]
	v_mfma_f32_16x16x32_bf16 v[64:67], v[198:201], v[230:233], v[64:67]
	v_mfma_f32_16x16x32_bf16 v[116:119], v[194:197], v[210:213], v[116:119]
	v_mfma_f32_16x16x32_bf16 v[112:115], v[202:205], v[210:213], v[112:115]
	v_mfma_f32_16x16x32_bf16 v[100:103], v[194:197], v[218:221], v[100:103]
	v_mfma_f32_16x16x32_bf16 v[96:99], v[202:205], v[218:221], v[96:99]
	v_mfma_f32_16x16x32_bf16 v[84:87], v[194:197], v[226:229], v[84:87]
	v_mfma_f32_16x16x32_bf16 v[80:83], v[202:205], v[226:229], v[80:83]
	v_mfma_f32_16x16x32_bf16 v[68:71], v[194:197], v[234:237], v[68:71]
	v_mfma_f32_16x16x32_bf16 v[64:67], v[202:205], v[234:237], v[64:67]
	s_setprio 0
	s_barrier
	s_add_i32 s16, s16, s52
	v_lshl_add_u64 v[146:147], v[146:147], 0, s[14:15]
	s_mov_b32 m0, s16
	ds_read_b128 v[206:209], v151 offset:49152
	ds_read_b128 v[210:213], v151 offset:50176
	ds_read_b128 v[214:217], v151 offset:51200
	ds_read_b128 v[218:221], v151 offset:52224
	ds_read_b128 v[222:225], v151 offset:53248
	ds_read_b128 v[226:229], v151 offset:54272
	ds_read_b128 v[230:233], v151 offset:55296
	ds_read_b128 v[234:237], v151 offset:56320
	global_load_lds_dwordx4 v[146:147], off
	s_add_i32 m0, s16, 0x2000
	s_add_u32 s48, s48, 0x40080
	v_lshl_add_u64 v[146:147], v[186:187], 0, s[14:15]
	s_addc_u32 s49, s49, 0
	s_add_i32 s16, s64, s52
	global_load_lds_dwordx4 v[146:147], off
	v_lshl_add_u64 v[146:147], s[48:49], 0, v[130:131]
	s_mov_b32 m0, s16
	s_nop 0
	global_load_lds_dwordx4 v[146:147], off
	v_lshl_add_u64 v[146:147], s[48:49], 0, v[134:135]
	s_add_i32 m0, s16, 0x2000
	s_nop 0
	global_load_lds_dwordx4 v[146:147], off
	v_lshl_add_u64 v[146:147], v[238:239], 0, s[14:15]
	s_mov_b32 m0, s59
	s_nop 0
	global_load_lds_dwordx4 v[146:147], off
	v_lshl_add_u64 v[146:147], v[240:241], 0, s[14:15]
	s_mov_b32 m0, s60
	s_nop 0
	global_load_lds_dwordx4 v[146:147], off
	s_waitcnt vmcnt(8)
	s_waitcnt lgkmcnt(0)
	s_barrier
	s_setprio 1
	s_waitcnt lgkmcnt(0)
	v_mfma_f32_16x16x32_bf16 v[60:63], v[170:173], v[206:209], v[60:63]
	v_mfma_f32_16x16x32_bf16 v[56:59], v[178:181], v[206:209], v[56:59]
	v_mfma_f32_16x16x32_bf16 v[44:47], v[170:173], v[214:217], v[44:47]
	v_mfma_f32_16x16x32_bf16 v[40:43], v[178:181], v[214:217], v[40:43]
	v_mfma_f32_16x16x32_bf16 v[28:31], v[170:173], v[222:225], v[28:31]
	v_mfma_f32_16x16x32_bf16 v[24:27], v[178:181], v[222:225], v[24:27]
	v_mfma_f32_16x16x32_bf16 v[12:15], v[170:173], v[230:233], v[12:15]
	v_mfma_f32_16x16x32_bf16 v[8:11], v[178:181], v[230:233], v[8:11]
	v_mfma_f32_16x16x32_bf16 v[60:63], v[174:177], v[210:213], v[60:63]
	v_mfma_f32_16x16x32_bf16 v[56:59], v[182:185], v[210:213], v[56:59]
	v_mfma_f32_16x16x32_bf16 v[44:47], v[174:177], v[218:221], v[44:47]
	v_mfma_f32_16x16x32_bf16 v[40:43], v[182:185], v[218:221], v[40:43]
	v_mfma_f32_16x16x32_bf16 v[28:31], v[174:177], v[226:229], v[28:31]
	v_mfma_f32_16x16x32_bf16 v[24:27], v[182:185], v[226:229], v[24:27]
	v_mfma_f32_16x16x32_bf16 v[12:15], v[174:177], v[234:237], v[12:15]
	v_mfma_f32_16x16x32_bf16 v[8:11], v[182:185], v[234:237], v[8:11]
	v_mfma_f32_16x16x32_bf16 v[52:55], v[190:193], v[206:209], v[52:55]
	v_mfma_f32_16x16x32_bf16 v[48:51], v[198:201], v[206:209], v[48:51]
	v_mfma_f32_16x16x32_bf16 v[36:39], v[190:193], v[214:217], v[36:39]
	v_mfma_f32_16x16x32_bf16 v[32:35], v[198:201], v[214:217], v[32:35]
	v_mfma_f32_16x16x32_bf16 v[20:23], v[190:193], v[222:225], v[20:23]
	v_mfma_f32_16x16x32_bf16 v[16:19], v[198:201], v[222:225], v[16:19]
	v_mfma_f32_16x16x32_bf16 v[4:7], v[190:193], v[230:233], v[4:7]
	v_mfma_f32_16x16x32_bf16 v[0:3], v[198:201], v[230:233], v[0:3]
	v_mfma_f32_16x16x32_bf16 v[52:55], v[194:197], v[210:213], v[52:55]
	v_mfma_f32_16x16x32_bf16 v[48:51], v[202:205], v[210:213], v[48:51]
	v_mfma_f32_16x16x32_bf16 v[36:39], v[194:197], v[218:221], v[36:39]
	v_mfma_f32_16x16x32_bf16 v[32:35], v[202:205], v[218:221], v[32:35]
	v_mfma_f32_16x16x32_bf16 v[20:23], v[194:197], v[226:229], v[20:23]
	v_mfma_f32_16x16x32_bf16 v[16:19], v[202:205], v[226:229], v[16:19]
	v_mfma_f32_16x16x32_bf16 v[4:7], v[194:197], v[234:237], v[4:7]
	v_mfma_f32_16x16x32_bf16 v[0:3], v[202:205], v[234:237], v[0:3]
	s_setprio 0
	s_barrier
	s_add_i32 s63, s63, 2
	s_add_u32 s46, s46, 0x100
	s_addc_u32 s47, s47, 0
	s_add_u32 s33, s33, 0x100
	s_addc_u32 s43, s43, 0
	s_cmp_gt_u32 s63, 13
	s_cbranch_scc1 .LBB0_603

.LBB0_684:
	s_ashr_i32 s21, s20, 31
	s_lshl_b64 s[22:23], s[20:21], 19
	s_add_u32 s22, s4, s22
	s_addc_u32 s23, s5, s23
	s_and_b64 s[24:25], s[0:1], exec
	s_cselect_b32 s19, s23, s41
	s_cselect_b32 s21, s22, s40
	s_ashr_i32 s15, s14, 31
	s_lshl_b64 s[24:25], s[14:15], 19
	s_add_u32 s24, s72, s24
	s_addc_u32 s25, s73, s25
	s_and_b64 s[42:43], s[0:1], exec
	s_cselect_b32 s15, s25, s39
	s_cselect_b32 s33, s24, s38
	v_lshl_add_u32 v0, s20, 8, v146
	s_add_u32 s57, s38, 0x100
	v_ashrrev_i32_e32 v1, 31, v0
	s_addc_u32 s58, s39, 0
	v_lshl_add_u64 v[144:145], v[0:1], 2, s[8:9]
	s_add_u32 s38, s40, 0x40080
	s_addc_u32 s39, s41, 0
	s_mov_b32 s59, -2
	s_waitcnt vmcnt(8)
	v_mov_b32_e32 v153, v166
	v_mov_b32_e32 v154, v165
	v_mov_b32_e32 v155, v164
	v_mov_b32_e32 v156, v163
	v_mov_b32_e32 v157, v162
	v_mov_b32_e32 v158, v161
	v_mov_b32_e32 v159, v152
	v_mov_b32_e32 v160, v149
	s_mov_b64 s[40:41], 0
	v_add_u32_e32 v167, s54, v147
	ds_read_b128 v[168:171], v167
	ds_read_b128 v[172:175], v167 offset:1024
	ds_read_b128 v[176:179], v167 offset:2048
	ds_read_b128 v[180:183], v167 offset:3072
	v_add_u32_e32 v167, s55, v147
	ds_read_b128 v[184:187], v167
	ds_read_b128 v[190:193], v167 offset:1024
	ds_read_b128 v[194:197], v167 offset:2048
	ds_read_b128 v[198:201], v167 offset:3072
	s_add_u32 s16, s38, 0xfffc0080
	s_addc_u32 s42, s39, -1
	s_and_b64 s[40:41], s[40:41], exec
	s_cselect_b32 s43, s19, s42
	s_cselect_b32 s42, s21, s16
	s_cselect_b32 s41, s15, s58
	s_cselect_b32 s40, s33, s57
	v_lshl_add_u64 v[234:235], s[38:39], 0, v[136:137]
	s_add_i32 m0, s37, 0xc000
	ds_read_b128 v[202:205], v150
	ds_read_b128 v[206:209], v150 offset:1024
	ds_read_b128 v[210:213], v150 offset:2048
	ds_read_b128 v[214:217], v150 offset:3072
	ds_read_b128 v[218:221], v150 offset:4096
	ds_read_b128 v[222:225], v150 offset:5120
	ds_read_b128 v[226:229], v150 offset:6144
	ds_read_b128 v[230:233], v150 offset:7168
	global_load_lds_dwordx4 v[234:235], off
	v_lshl_add_u64 v[234:235], s[38:39], 0, v[138:139]
	s_add_i32 m0, s37, 0xe000
	s_nop 0
	global_load_lds_dwordx4 v[234:235], off
	s_waitcnt vmcnt(8)
	s_waitcnt lgkmcnt(0)
	s_barrier
	s_setprio 1
	s_waitcnt lgkmcnt(0)
	v_mfma_f32_16x16x32_bf16 v[124:127], v[168:171], v[202:205], 0
	v_mfma_f32_16x16x32_bf16 v[116:119], v[176:179], v[202:205], 0
	v_mfma_f32_16x16x32_bf16 v[108:111], v[168:171], v[210:213], 0
	v_mfma_f32_16x16x32_bf16 v[100:103], v[176:179], v[210:213], 0
	v_mfma_f32_16x16x32_bf16 v[92:95], v[168:171], v[218:221], 0
	v_mfma_f32_16x16x32_bf16 v[84:87], v[176:179], v[218:221], 0
	v_mfma_f32_16x16x32_bf16 v[76:79], v[168:171], v[226:229], 0
	v_mfma_f32_16x16x32_bf16 v[68:71], v[176:179], v[226:229], 0
	v_mfma_f32_16x16x32_bf16 v[124:127], v[172:175], v[206:209], v[124:127]
	v_mfma_f32_16x16x32_bf16 v[116:119], v[180:183], v[206:209], v[116:119]
	v_mfma_f32_16x16x32_bf16 v[108:111], v[172:175], v[214:217], v[108:111]
	v_mfma_f32_16x16x32_bf16 v[100:103], v[180:183], v[214:217], v[100:103]
	v_mfma_f32_16x16x32_bf16 v[92:95], v[172:175], v[222:225], v[92:95]
	v_mfma_f32_16x16x32_bf16 v[84:87], v[180:183], v[222:225], v[84:87]
	v_mfma_f32_16x16x32_bf16 v[76:79], v[172:175], v[230:233], v[76:79]
	v_mfma_f32_16x16x32_bf16 v[68:71], v[180:183], v[230:233], v[68:71]
	v_mfma_f32_16x16x32_bf16 v[120:123], v[184:187], v[202:205], 0
	v_mfma_f32_16x16x32_bf16 v[112:115], v[194:197], v[202:205], 0
	v_mfma_f32_16x16x32_bf16 v[104:107], v[184:187], v[210:213], 0
	v_mfma_f32_16x16x32_bf16 v[96:99], v[194:197], v[210:213], 0
	v_mfma_f32_16x16x32_bf16 v[88:91], v[184:187], v[218:221], 0
	v_mfma_f32_16x16x32_bf16 v[80:83], v[194:197], v[218:221], 0
	v_mfma_f32_16x16x32_bf16 v[72:75], v[184:187], v[226:229], 0
	v_mfma_f32_16x16x32_bf16 v[64:67], v[194:197], v[226:229], 0
	v_mfma_f32_16x16x32_bf16 v[120:123], v[190:193], v[206:209], v[120:123]
	v_mfma_f32_16x16x32_bf16 v[112:115], v[198:201], v[206:209], v[112:115]
	v_mfma_f32_16x16x32_bf16 v[104:107], v[190:193], v[214:217], v[104:107]
	v_mfma_f32_16x16x32_bf16 v[96:99], v[198:201], v[214:217], v[96:99]
	v_mfma_f32_16x16x32_bf16 v[88:91], v[190:193], v[222:225], v[88:91]
	v_mfma_f32_16x16x32_bf16 v[80:83], v[198:201], v[222:225], v[80:83]
	v_mfma_f32_16x16x32_bf16 v[72:75], v[190:193], v[230:233], v[72:75]
	v_mfma_f32_16x16x32_bf16 v[64:67], v[198:201], v[230:233], v[64:67]
	s_setprio 0
	s_barrier
	s_add_i32 s16, s54, s44
	v_lshl_add_u64 v[234:235], s[40:41], 0, v[130:131]
	s_mov_b32 m0, s16
	ds_read_b128 v[202:205], v150 offset:16384
	ds_read_b128 v[206:209], v150 offset:17408
	ds_read_b128 v[210:213], v150 offset:18432
	ds_read_b128 v[214:217], v150 offset:19456
	ds_read_b128 v[218:221], v150 offset:20480
	ds_read_b128 v[222:225], v150 offset:21504
	ds_read_b128 v[226:229], v150 offset:22528
	ds_read_b128 v[230:233], v150 offset:23552
	global_load_lds_dwordx4 v[234:235], off
	s_add_i32 m0, s16, 0x2000
	s_add_u32 s60, s40, 0x40000
	v_lshl_add_u64 v[236:237], s[40:41], 0, v[134:135]
	s_addc_u32 s61, s41, 0
	s_add_i32 s16, s55, s44
	global_load_lds_dwordx4 v[236:237], off
	v_lshl_add_u64 v[238:239], s[60:61], 0, v[130:131]
	s_mov_b32 m0, s16
	v_lshl_add_u64 v[240:241], s[42:43], 0, v[132:133]
	global_load_lds_dwordx4 v[238:239], off
	v_lshl_add_u64 v[238:239], s[60:61], 0, v[134:135]
	s_add_i32 m0, s16, 0x2000
	s_nop 0
	global_load_lds_dwordx4 v[238:239], off
	v_lshl_add_u64 v[238:239], s[42:43], 0, v[128:129]
	s_mov_b32 m0, s37
	s_nop 0
	global_load_lds_dwordx4 v[238:239], off
	s_mov_b32 m0, s47
	s_nop 0
	global_load_lds_dwordx4 v[240:241], off
	s_waitcnt vmcnt(8)
	s_waitcnt lgkmcnt(0)
	s_barrier
	s_setprio 1
	s_waitcnt lgkmcnt(0)
	v_mfma_f32_16x16x32_bf16 v[60:63], v[168:171], v[202:205], 0
	v_mfma_f32_16x16x32_bf16 v[52:55], v[176:179], v[202:205], 0
	v_mfma_f32_16x16x32_bf16 v[44:47], v[168:171], v[210:213], 0
	v_mfma_f32_16x16x32_bf16 v[36:39], v[176:179], v[210:213], 0
	v_mfma_f32_16x16x32_bf16 v[28:31], v[168:171], v[218:221], 0
	v_mfma_f32_16x16x32_bf16 v[20:23], v[176:179], v[218:221], 0
	v_mfma_f32_16x16x32_bf16 v[12:15], v[168:171], v[226:229], 0
	v_mfma_f32_16x16x32_bf16 v[4:7], v[176:179], v[226:229], 0
	v_mfma_f32_16x16x32_bf16 v[60:63], v[172:175], v[206:209], v[60:63]
	v_mfma_f32_16x16x32_bf16 v[52:55], v[180:183], v[206:209], v[52:55]
	v_mfma_f32_16x16x32_bf16 v[44:47], v[172:175], v[214:217], v[44:47]
	v_mfma_f32_16x16x32_bf16 v[36:39], v[180:183], v[214:217], v[36:39]
	v_mfma_f32_16x16x32_bf16 v[28:31], v[172:175], v[222:225], v[28:31]
	v_mfma_f32_16x16x32_bf16 v[20:23], v[180:183], v[222:225], v[20:23]
	v_mfma_f32_16x16x32_bf16 v[12:15], v[172:175], v[230:233], v[12:15]
	v_mfma_f32_16x16x32_bf16 v[4:7], v[180:183], v[230:233], v[4:7]
	v_mfma_f32_16x16x32_bf16 v[56:59], v[184:187], v[202:205], 0
	v_mfma_f32_16x16x32_bf16 v[48:51], v[194:197], v[202:205], 0
	v_mfma_f32_16x16x32_bf16 v[40:43], v[184:187], v[210:213], 0
	v_mfma_f32_16x16x32_bf16 v[32:35], v[194:197], v[210:213], 0
	v_mfma_f32_16x16x32_bf16 v[24:27], v[184:187], v[218:221], 0
	v_mfma_f32_16x16x32_bf16 v[16:19], v[194:197], v[218:221], 0
	v_mfma_f32_16x16x32_bf16 v[8:11], v[184:187], v[226:229], 0
	v_mfma_f32_16x16x32_bf16 v[0:3], v[194:197], v[226:229], 0
	v_mfma_f32_16x16x32_bf16 v[56:59], v[190:193], v[206:209], v[56:59]
	v_mfma_f32_16x16x32_bf16 v[48:51], v[198:201], v[206:209], v[48:51]
	v_mfma_f32_16x16x32_bf16 v[40:43], v[190:193], v[214:217], v[40:43]
	v_mfma_f32_16x16x32_bf16 v[32:35], v[198:201], v[214:217], v[32:35]
	v_mfma_f32_16x16x32_bf16 v[24:27], v[190:193], v[222:225], v[24:27]
	v_mfma_f32_16x16x32_bf16 v[16:19], v[198:201], v[222:225], v[16:19]
	v_mfma_f32_16x16x32_bf16 v[8:11], v[190:193], v[230:233], v[8:11]
	v_mfma_f32_16x16x32_bf16 v[0:3], v[198:201], v[230:233], v[0:3]
	s_setprio 0
	s_barrier
	s_branch .Lpeelp6_mid
.LBB0_685:
	v_add_u32_e32 v167, s54, v147
	ds_read_b128 v[168:171], v167
	ds_read_b128 v[172:175], v167 offset:1024
	ds_read_b128 v[176:179], v167 offset:2048
	ds_read_b128 v[180:183], v167 offset:3072
	v_add_u32_e32 v167, s55, v147
	ds_read_b128 v[184:187], v167
	ds_read_b128 v[190:193], v167 offset:1024
	ds_read_b128 v[194:197], v167 offset:2048
	ds_read_b128 v[198:201], v167 offset:3072
	s_add_u32 s16, s38, 0xfffc0080
	s_addc_u32 s42, s39, -1
	s_and_b64 s[40:41], s[40:41], exec
	s_cselect_b32 s43, s19, s42
	s_cselect_b32 s42, s21, s16
	s_cselect_b32 s41, s15, s58
	s_cselect_b32 s40, s33, s57
	v_lshl_add_u64 v[234:235], s[38:39], 0, v[136:137]
	s_add_i32 m0, s37, 0xc000
	ds_read_b128 v[202:205], v150
	ds_read_b128 v[206:209], v150 offset:1024
	ds_read_b128 v[210:213], v150 offset:2048
	ds_read_b128 v[214:217], v150 offset:3072
	ds_read_b128 v[218:221], v150 offset:4096
	ds_read_b128 v[222:225], v150 offset:5120
	ds_read_b128 v[226:229], v150 offset:6144
	ds_read_b128 v[230:233], v150 offset:7168
	global_load_lds_dwordx4 v[234:235], off
	v_lshl_add_u64 v[234:235], s[38:39], 0, v[138:139]
	s_add_i32 m0, s37, 0xe000
	s_nop 0
	global_load_lds_dwordx4 v[234:235], off
	s_waitcnt vmcnt(8)
	s_waitcnt lgkmcnt(0)
	s_barrier
	s_setprio 1
	s_waitcnt lgkmcnt(0)
	v_mfma_f32_16x16x32_bf16 v[124:127], v[168:171], v[202:205], v[124:127]
	v_mfma_f32_16x16x32_bf16 v[116:119], v[176:179], v[202:205], v[116:119]
	v_mfma_f32_16x16x32_bf16 v[108:111], v[168:171], v[210:213], v[108:111]
	v_mfma_f32_16x16x32_bf16 v[100:103], v[176:179], v[210:213], v[100:103]
	v_mfma_f32_16x16x32_bf16 v[92:95], v[168:171], v[218:221], v[92:95]
	v_mfma_f32_16x16x32_bf16 v[84:87], v[176:179], v[218:221], v[84:87]
	v_mfma_f32_16x16x32_bf16 v[76:79], v[168:171], v[226:229], v[76:79]
	v_mfma_f32_16x16x32_bf16 v[68:71], v[176:179], v[226:229], v[68:71]
	v_mfma_f32_16x16x32_bf16 v[124:127], v[172:175], v[206:209], v[124:127]
	v_mfma_f32_16x16x32_bf16 v[116:119], v[180:183], v[206:209], v[116:119]
	v_mfma_f32_16x16x32_bf16 v[108:111], v[172:175], v[214:217], v[108:111]
	v_mfma_f32_16x16x32_bf16 v[100:103], v[180:183], v[214:217], v[100:103]
	v_mfma_f32_16x16x32_bf16 v[92:95], v[172:175], v[222:225], v[92:95]
	v_mfma_f32_16x16x32_bf16 v[84:87], v[180:183], v[222:225], v[84:87]
	v_mfma_f32_16x16x32_bf16 v[76:79], v[172:175], v[230:233], v[76:79]
	v_mfma_f32_16x16x32_bf16 v[68:71], v[180:183], v[230:233], v[68:71]
	v_mfma_f32_16x16x32_bf16 v[120:123], v[184:187], v[202:205], v[120:123]
	v_mfma_f32_16x16x32_bf16 v[112:115], v[194:197], v[202:205], v[112:115]
	v_mfma_f32_16x16x32_bf16 v[104:107], v[184:187], v[210:213], v[104:107]
	v_mfma_f32_16x16x32_bf16 v[96:99], v[194:197], v[210:213], v[96:99]
	v_mfma_f32_16x16x32_bf16 v[88:91], v[184:187], v[218:221], v[88:91]
	v_mfma_f32_16x16x32_bf16 v[80:83], v[194:197], v[218:221], v[80:83]
	v_mfma_f32_16x16x32_bf16 v[72:75], v[184:187], v[226:229], v[72:75]
	v_mfma_f32_16x16x32_bf16 v[64:67], v[194:197], v[226:229], v[64:67]
	v_mfma_f32_16x16x32_bf16 v[120:123], v[190:193], v[206:209], v[120:123]
	v_mfma_f32_16x16x32_bf16 v[112:115], v[198:201], v[206:209], v[112:115]
	v_mfma_f32_16x16x32_bf16 v[104:107], v[190:193], v[214:217], v[104:107]
	v_mfma_f32_16x16x32_bf16 v[96:99], v[198:201], v[214:217], v[96:99]
	v_mfma_f32_16x16x32_bf16 v[88:91], v[190:193], v[222:225], v[88:91]
	v_mfma_f32_16x16x32_bf16 v[80:83], v[198:201], v[222:225], v[80:83]
	v_mfma_f32_16x16x32_bf16 v[72:75], v[190:193], v[230:233], v[72:75]
	v_mfma_f32_16x16x32_bf16 v[64:67], v[198:201], v[230:233], v[64:67]
	s_setprio 0
	s_barrier
	s_add_i32 s16, s54, s44
	v_lshl_add_u64 v[234:235], s[40:41], 0, v[130:131]
	s_mov_b32 m0, s16
	ds_read_b128 v[202:205], v150 offset:16384
	ds_read_b128 v[206:209], v150 offset:17408
	ds_read_b128 v[210:213], v150 offset:18432
	ds_read_b128 v[214:217], v150 offset:19456
	ds_read_b128 v[218:221], v150 offset:20480
	ds_read_b128 v[222:225], v150 offset:21504
	ds_read_b128 v[226:229], v150 offset:22528
	ds_read_b128 v[230:233], v150 offset:23552
	global_load_lds_dwordx4 v[234:235], off
	s_add_i32 m0, s16, 0x2000
	s_add_u32 s60, s40, 0x40000
	v_lshl_add_u64 v[236:237], s[40:41], 0, v[134:135]
	s_addc_u32 s61, s41, 0
	s_add_i32 s16, s55, s44
	global_load_lds_dwordx4 v[236:237], off
	v_lshl_add_u64 v[238:239], s[60:61], 0, v[130:131]
	s_mov_b32 m0, s16
	v_lshl_add_u64 v[240:241], s[42:43], 0, v[132:133]
	global_load_lds_dwordx4 v[238:239], off
	v_lshl_add_u64 v[238:239], s[60:61], 0, v[134:135]
	s_add_i32 m0, s16, 0x2000
	s_nop 0
	global_load_lds_dwordx4 v[238:239], off
	v_lshl_add_u64 v[238:239], s[42:43], 0, v[128:129]
	s_mov_b32 m0, s37
	s_nop 0
	global_load_lds_dwordx4 v[238:239], off
	s_mov_b32 m0, s47
	s_nop 0
	global_load_lds_dwordx4 v[240:241], off
	s_waitcnt vmcnt(8)
	s_waitcnt lgkmcnt(0)
	s_barrier
	s_setprio 1
	s_waitcnt lgkmcnt(0)
	v_mfma_f32_16x16x32_bf16 v[60:63], v[168:171], v[202:205], v[60:63]
	v_mfma_f32_16x16x32_bf16 v[52:55], v[176:179], v[202:205], v[52:55]
	v_mfma_f32_16x16x32_bf16 v[44:47], v[168:171], v[210:213], v[44:47]
	v_mfma_f32_16x16x32_bf16 v[36:39], v[176:179], v[210:213], v[36:39]
	v_mfma_f32_16x16x32_bf16 v[28:31], v[168:171], v[218:221], v[28:31]
	v_mfma_f32_16x16x32_bf16 v[20:23], v[176:179], v[218:221], v[20:23]
	v_mfma_f32_16x16x32_bf16 v[12:15], v[168:171], v[226:229], v[12:15]
	v_mfma_f32_16x16x32_bf16 v[4:7], v[176:179], v[226:229], v[4:7]
	v_mfma_f32_16x16x32_bf16 v[60:63], v[172:175], v[206:209], v[60:63]
	v_mfma_f32_16x16x32_bf16 v[52:55], v[180:183], v[206:209], v[52:55]
	v_mfma_f32_16x16x32_bf16 v[44:47], v[172:175], v[214:217], v[44:47]
	v_mfma_f32_16x16x32_bf16 v[36:39], v[180:183], v[214:217], v[36:39]
	v_mfma_f32_16x16x32_bf16 v[28:31], v[172:175], v[222:225], v[28:31]
	v_mfma_f32_16x16x32_bf16 v[20:23], v[180:183], v[222:225], v[20:23]
	v_mfma_f32_16x16x32_bf16 v[12:15], v[172:175], v[230:233], v[12:15]
	v_mfma_f32_16x16x32_bf16 v[4:7], v[180:183], v[230:233], v[4:7]
	v_mfma_f32_16x16x32_bf16 v[56:59], v[184:187], v[202:205], v[56:59]
	v_mfma_f32_16x16x32_bf16 v[48:51], v[194:197], v[202:205], v[48:51]
	v_mfma_f32_16x16x32_bf16 v[40:43], v[184:187], v[210:213], v[40:43]
	v_mfma_f32_16x16x32_bf16 v[32:35], v[194:197], v[210:213], v[32:35]
	v_mfma_f32_16x16x32_bf16 v[24:27], v[184:187], v[218:221], v[24:27]
	v_mfma_f32_16x16x32_bf16 v[16:19], v[194:197], v[218:221], v[16:19]
	v_mfma_f32_16x16x32_bf16 v[8:11], v[184:187], v[226:229], v[8:11]
	v_mfma_f32_16x16x32_bf16 v[0:3], v[194:197], v[226:229], v[0:3]
	v_mfma_f32_16x16x32_bf16 v[56:59], v[190:193], v[206:209], v[56:59]
	v_mfma_f32_16x16x32_bf16 v[48:51], v[198:201], v[206:209], v[48:51]
	v_mfma_f32_16x16x32_bf16 v[40:43], v[190:193], v[214:217], v[40:43]
	v_mfma_f32_16x16x32_bf16 v[32:35], v[198:201], v[214:217], v[32:35]
	v_mfma_f32_16x16x32_bf16 v[24:27], v[190:193], v[222:225], v[24:27]
	v_mfma_f32_16x16x32_bf16 v[16:19], v[198:201], v[222:225], v[16:19]
	v_mfma_f32_16x16x32_bf16 v[8:11], v[190:193], v[230:233], v[8:11]
	v_mfma_f32_16x16x32_bf16 v[0:3], v[198:201], v[230:233], v[0:3]
	s_setprio 0
	s_barrier
.Lpeelp6_mid:
	s_add_i32 s16, 0, 0x18000
	v_add_u32_e32 v167, s16, v147
	s_add_i32 s60, 0, 0x1c000
	ds_read_b128 v[168:171], v167
	ds_read_b128 v[172:175], v167 offset:1024
	ds_read_b128 v[176:179], v167 offset:2048
	ds_read_b128 v[180:183], v167 offset:3072
	v_add_u32_e32 v167, s60, v147
	ds_read_b128 v[184:187], v167
	ds_read_b128 v[190:193], v167 offset:1024
	ds_read_b128 v[194:197], v167 offset:2048
	ds_read_b128 v[198:201], v167 offset:3072
	s_add_u32 s42, s42, 0x40000
	s_addc_u32 s43, s43, 0
	s_mov_b32 m0, s48
	v_lshl_add_u64 v[242:243], s[42:43], 0, v[128:129]
	ds_read_b128 v[202:205], v150 offset:32768
	ds_read_b128 v[206:209], v150 offset:33792
	ds_read_b128 v[210:213], v150 offset:34816
	ds_read_b128 v[214:217], v150 offset:35840
	ds_read_b128 v[218:221], v150 offset:36864
	ds_read_b128 v[222:225], v150 offset:37888
	ds_read_b128 v[226:229], v150 offset:38912
	ds_read_b128 v[230:233], v150 offset:39936
	global_load_lds_dwordx4 v[242:243], off
	v_lshl_add_u64 v[242:243], s[42:43], 0, v[132:133]
	s_mov_b32 m0, s49
	s_nop 0
	global_load_lds_dwordx4 v[242:243], off
	s_waitcnt vmcnt(8)
	s_waitcnt lgkmcnt(0)
	s_barrier
	s_setprio 1
	s_waitcnt lgkmcnt(0)
	v_mfma_f32_16x16x32_bf16 v[124:127], v[168:171], v[202:205], v[124:127]
	v_mfma_f32_16x16x32_bf16 v[116:119], v[176:179], v[202:205], v[116:119]
	v_mfma_f32_16x16x32_bf16 v[108:111], v[168:171], v[210:213], v[108:111]
	v_mfma_f32_16x16x32_bf16 v[100:103], v[176:179], v[210:213], v[100:103]
	v_mfma_f32_16x16x32_bf16 v[92:95], v[168:171], v[218:221], v[92:95]
	v_mfma_f32_16x16x32_bf16 v[84:87], v[176:179], v[218:221], v[84:87]
	v_mfma_f32_16x16x32_bf16 v[76:79], v[168:171], v[226:229], v[76:79]
	v_mfma_f32_16x16x32_bf16 v[68:71], v[176:179], v[226:229], v[68:71]
	v_mfma_f32_16x16x32_bf16 v[124:127], v[172:175], v[206:209], v[124:127]
	v_mfma_f32_16x16x32_bf16 v[116:119], v[180:183], v[206:209], v[116:119]
	v_mfma_f32_16x16x32_bf16 v[108:111], v[172:175], v[214:217], v[108:111]
	v_mfma_f32_16x16x32_bf16 v[100:103], v[180:183], v[214:217], v[100:103]
	v_mfma_f32_16x16x32_bf16 v[92:95], v[172:175], v[222:225], v[92:95]
	v_mfma_f32_16x16x32_bf16 v[84:87], v[180:183], v[222:225], v[84:87]
	v_mfma_f32_16x16x32_bf16 v[76:79], v[172:175], v[230:233], v[76:79]
	v_mfma_f32_16x16x32_bf16 v[68:71], v[180:183], v[230:233], v[68:71]
	v_mfma_f32_16x16x32_bf16 v[120:123], v[184:187], v[202:205], v[120:123]
	v_mfma_f32_16x16x32_bf16 v[112:115], v[194:197], v[202:205], v[112:115]
	v_mfma_f32_16x16x32_bf16 v[104:107], v[184:187], v[210:213], v[104:107]
	v_mfma_f32_16x16x32_bf16 v[96:99], v[194:197], v[210:213], v[96:99]
	v_mfma_f32_16x16x32_bf16 v[88:91], v[184:187], v[218:221], v[88:91]
	v_mfma_f32_16x16x32_bf16 v[80:83], v[194:197], v[218:221], v[80:83]
	v_mfma_f32_16x16x32_bf16 v[72:75], v[184:187], v[226:229], v[72:75]
	v_mfma_f32_16x16x32_bf16 v[64:67], v[194:197], v[226:229], v[64:67]
	v_mfma_f32_16x16x32_bf16 v[120:123], v[190:193], v[206:209], v[120:123]
	v_mfma_f32_16x16x32_bf16 v[112:115], v[198:201], v[206:209], v[112:115]
	v_mfma_f32_16x16x32_bf16 v[104:107], v[190:193], v[214:217], v[104:107]
	v_mfma_f32_16x16x32_bf16 v[96:99], v[198:201], v[214:217], v[96:99]
	v_mfma_f32_16x16x32_bf16 v[88:91], v[190:193], v[222:225], v[88:91]
	v_mfma_f32_16x16x32_bf16 v[80:83], v[198:201], v[222:225], v[80:83]
	v_mfma_f32_16x16x32_bf16 v[72:75], v[190:193], v[230:233], v[72:75]
	v_mfma_f32_16x16x32_bf16 v[64:67], v[198:201], v[230:233], v[64:67]
	s_setprio 0
	s_barrier
	s_add_i32 s16, s16, s44
	v_lshl_add_u64 v[234:235], v[234:235], 0, s[10:11]
	s_mov_b32 m0, s16
	ds_read_b128 v[202:205], v150 offset:49152
	ds_read_b128 v[206:209], v150 offset:50176
	ds_read_b128 v[210:213], v150 offset:51200
	ds_read_b128 v[214:217], v150 offset:52224
	ds_read_b128 v[218:221], v150 offset:53248
	ds_read_b128 v[222:225], v150 offset:54272
	ds_read_b128 v[226:229], v150 offset:55296
	ds_read_b128 v[230:233], v150 offset:56320
	global_load_lds_dwordx4 v[234:235], off
	s_add_i32 m0, s16, 0x2000
	s_add_u32 s40, s40, 0x40080
	v_lshl_add_u64 v[234:235], v[236:237], 0, s[10:11]
	s_addc_u32 s41, s41, 0
	s_add_i32 s16, s60, s44
	global_load_lds_dwordx4 v[234:235], off
	v_lshl_add_u64 v[234:235], s[40:41], 0, v[130:131]
	s_mov_b32 m0, s16
	s_nop 0
	global_load_lds_dwordx4 v[234:235], off
	v_lshl_add_u64 v[234:235], s[40:41], 0, v[134:135]
	s_add_i32 m0, s16, 0x2000
	s_nop 0
	global_load_lds_dwordx4 v[234:235], off
	v_lshl_add_u64 v[234:235], v[238:239], 0, s[10:11]
	s_mov_b32 m0, s52
	s_nop 0
	global_load_lds_dwordx4 v[234:235], off
	v_lshl_add_u64 v[234:235], v[240:241], 0, s[10:11]
	s_mov_b32 m0, s53
	s_nop 0
	global_load_lds_dwordx4 v[234:235], off
	s_waitcnt vmcnt(8)
	s_waitcnt lgkmcnt(0)
	s_barrier
	s_setprio 1
	s_waitcnt lgkmcnt(0)
	v_mfma_f32_16x16x32_bf16 v[60:63], v[168:171], v[202:205], v[60:63]
	v_mfma_f32_16x16x32_bf16 v[52:55], v[176:179], v[202:205], v[52:55]
	v_mfma_f32_16x16x32_bf16 v[44:47], v[168:171], v[210:213], v[44:47]
	v_mfma_f32_16x16x32_bf16 v[36:39], v[176:179], v[210:213], v[36:39]
	v_mfma_f32_16x16x32_bf16 v[28:31], v[168:171], v[218:221], v[28:31]
	v_mfma_f32_16x16x32_bf16 v[20:23], v[176:179], v[218:221], v[20:23]
	v_mfma_f32_16x16x32_bf16 v[12:15], v[168:171], v[226:229], v[12:15]
	v_mfma_f32_16x16x32_bf16 v[4:7], v[176:179], v[226:229], v[4:7]
	v_mfma_f32_16x16x32_bf16 v[60:63], v[172:175], v[206:209], v[60:63]
	v_mfma_f32_16x16x32_bf16 v[52:55], v[180:183], v[206:209], v[52:55]
	v_mfma_f32_16x16x32_bf16 v[44:47], v[172:175], v[214:217], v[44:47]
	v_mfma_f32_16x16x32_bf16 v[36:39], v[180:183], v[214:217], v[36:39]
	v_mfma_f32_16x16x32_bf16 v[28:31], v[172:175], v[222:225], v[28:31]
	v_mfma_f32_16x16x32_bf16 v[20:23], v[180:183], v[222:225], v[20:23]
	v_mfma_f32_16x16x32_bf16 v[12:15], v[172:175], v[230:233], v[12:15]
	v_mfma_f32_16x16x32_bf16 v[4:7], v[180:183], v[230:233], v[4:7]
	v_mfma_f32_16x16x32_bf16 v[56:59], v[184:187], v[202:205], v[56:59]
	v_mfma_f32_16x16x32_bf16 v[48:51], v[194:197], v[202:205], v[48:51]
	v_mfma_f32_16x16x32_bf16 v[40:43], v[184:187], v[210:213], v[40:43]
	v_mfma_f32_16x16x32_bf16 v[32:35], v[194:197], v[210:213], v[32:35]
	v_mfma_f32_16x16x32_bf16 v[24:27], v[184:187], v[218:221], v[24:27]
	v_mfma_f32_16x16x32_bf16 v[16:19], v[194:197], v[218:221], v[16:19]
	v_mfma_f32_16x16x32_bf16 v[8:11], v[184:187], v[226:229], v[8:11]
	v_mfma_f32_16x16x32_bf16 v[0:3], v[194:197], v[226:229], v[0:3]
	v_mfma_f32_16x16x32_bf16 v[56:59], v[190:193], v[206:209], v[56:59]
	v_mfma_f32_16x16x32_bf16 v[48:51], v[198:201], v[206:209], v[48:51]
	v_mfma_f32_16x16x32_bf16 v[40:43], v[190:193], v[214:217], v[40:43]
	v_mfma_f32_16x16x32_bf16 v[32:35], v[198:201], v[214:217], v[32:35]
	v_mfma_f32_16x16x32_bf16 v[24:27], v[190:193], v[222:225], v[24:27]
	v_mfma_f32_16x16x32_bf16 v[16:19], v[198:201], v[222:225], v[16:19]
	v_mfma_f32_16x16x32_bf16 v[8:11], v[190:193], v[230:233], v[8:11]
	v_mfma_f32_16x16x32_bf16 v[0:3], v[198:201], v[230:233], v[0:3]
	s_setprio 0
	s_barrier
	s_add_i32 s59, s59, 2
	s_add_u32 s57, s57, 0x100
	s_addc_u32 s58, s58, 0
	s_add_u32 s38, s38, 0x100
	s_addc_u32 s39, s39, 0
	s_cmp_gt_u32 s59, 13
	s_cbranch_scc1 .LBB0_688

.LBB0_761:
	s_add_u32 s28, s28, 0xb0080
	s_addc_u32 s29, s29, 0
	s_add_u32 s51, s30, 0x100
	s_addc_u32 s52, s31, 0
	s_mov_b32 s53, -2
	ds_read_b128 v[144:147], v153
	ds_read_b128 v[156:159], v153 offset:1024
	ds_read_b128 v[160:163], v153 offset:2048
	ds_read_b128 v[164:167], v153 offset:3072
	ds_read_b128 v[168:171], v154
	ds_read_b128 v[172:175], v154 offset:1024
	ds_read_b128 v[176:179], v154 offset:2048
	ds_read_b128 v[180:183], v154 offset:3072
	s_add_u32 s16, s28, 0xfff50080
	s_addc_u32 s30, s29, -1
	s_cmp_eq_u32 s53, 40
	s_cselect_b32 s37, s3, s30
	s_cselect_b32 s36, s2, s16
	s_cselect_b32 s31, s25, s52
	s_cselect_b32 s30, s24, s51
	v_lshl_add_u64 v[148:149], s[28:29], 0, v[136:137]
	s_add_i32 m0, s39, 0xc000
	ds_read_b128 v[184:187], v155
	ds_read_b128 v[188:191], v155 offset:1024
	ds_read_b128 v[192:195], v155 offset:2048
	ds_read_b128 v[196:199], v155 offset:3072
	ds_read_b128 v[200:203], v155 offset:4096
	ds_read_b128 v[204:207], v155 offset:5120
	ds_read_b128 v[208:211], v155 offset:6144
	ds_read_b128 v[212:215], v155 offset:7168
	global_load_lds_dwordx4 v[148:149], off
	v_lshl_add_u64 v[148:149], s[28:29], 0, v[138:139]
	s_add_i32 m0, s39, 0xe000
	s_nop 0
	global_load_lds_dwordx4 v[148:149], off
	s_waitcnt vmcnt(8)
	s_waitcnt lgkmcnt(0)
	s_barrier
	s_setprio 1
	s_waitcnt lgkmcnt(0)
	v_mfma_f32_16x16x32_bf16 v[124:127], v[144:147], v[184:187], 0
	v_mfma_f32_16x16x32_bf16 v[120:123], v[160:163], v[184:187], 0
	v_mfma_f32_16x16x32_bf16 v[116:119], v[144:147], v[192:195], 0
	v_mfma_f32_16x16x32_bf16 v[104:107], v[160:163], v[192:195], 0
	v_mfma_f32_16x16x32_bf16 v[100:103], v[144:147], v[200:203], 0
	v_mfma_f32_16x16x32_bf16 v[88:91], v[160:163], v[200:203], 0
	v_mfma_f32_16x16x32_bf16 v[84:87], v[144:147], v[208:211], 0
	v_mfma_f32_16x16x32_bf16 v[72:75], v[160:163], v[208:211], 0
	v_mfma_f32_16x16x32_bf16 v[124:127], v[156:159], v[188:191], v[124:127]
	v_mfma_f32_16x16x32_bf16 v[120:123], v[164:167], v[188:191], v[120:123]
	v_mfma_f32_16x16x32_bf16 v[116:119], v[156:159], v[196:199], v[116:119]
	v_mfma_f32_16x16x32_bf16 v[104:107], v[164:167], v[196:199], v[104:107]
	v_mfma_f32_16x16x32_bf16 v[100:103], v[156:159], v[204:207], v[100:103]
	v_mfma_f32_16x16x32_bf16 v[88:91], v[164:167], v[204:207], v[88:91]
	v_mfma_f32_16x16x32_bf16 v[84:87], v[156:159], v[212:215], v[84:87]
	v_mfma_f32_16x16x32_bf16 v[72:75], v[164:167], v[212:215], v[72:75]
	v_mfma_f32_16x16x32_bf16 v[112:115], v[168:171], v[184:187], 0
	v_mfma_f32_16x16x32_bf16 v[108:111], v[176:179], v[184:187], 0
	v_mfma_f32_16x16x32_bf16 v[96:99], v[168:171], v[192:195], 0
	v_mfma_f32_16x16x32_bf16 v[92:95], v[176:179], v[192:195], 0
	v_mfma_f32_16x16x32_bf16 v[80:83], v[168:171], v[200:203], 0
	v_mfma_f32_16x16x32_bf16 v[76:79], v[176:179], v[200:203], 0
	v_mfma_f32_16x16x32_bf16 v[68:71], v[168:171], v[208:211], 0
	v_mfma_f32_16x16x32_bf16 v[64:67], v[176:179], v[208:211], 0
	v_mfma_f32_16x16x32_bf16 v[112:115], v[172:175], v[188:191], v[112:115]
	v_mfma_f32_16x16x32_bf16 v[108:111], v[180:183], v[188:191], v[108:111]
	v_mfma_f32_16x16x32_bf16 v[96:99], v[172:175], v[196:199], v[96:99]
	v_mfma_f32_16x16x32_bf16 v[92:95], v[180:183], v[196:199], v[92:95]
	v_mfma_f32_16x16x32_bf16 v[80:83], v[172:175], v[204:207], v[80:83]
	v_mfma_f32_16x16x32_bf16 v[76:79], v[180:183], v[204:207], v[76:79]
	v_mfma_f32_16x16x32_bf16 v[68:71], v[172:175], v[212:215], v[68:71]
	v_mfma_f32_16x16x32_bf16 v[64:67], v[180:183], v[212:215], v[64:67]
	s_setprio 0
	s_barrier
	s_add_i32 s16, s47, s33
	v_lshl_add_u64 v[148:149], s[30:31], 0, v[130:131]
	s_mov_b32 m0, s16
	ds_read_b128 v[184:187], v155 offset:16384
	ds_read_b128 v[188:191], v155 offset:17408
	ds_read_b128 v[192:195], v155 offset:18432
	ds_read_b128 v[196:199], v155 offset:19456
	ds_read_b128 v[200:203], v155 offset:20480
	ds_read_b128 v[204:207], v155 offset:21504
	ds_read_b128 v[208:211], v155 offset:22528
	ds_read_b128 v[212:215], v155 offset:23552
	global_load_lds_dwordx4 v[148:149], off
	s_add_i32 m0, s16, 0x2000
	s_add_u32 s54, s30, 0xb0000
	v_lshl_add_u64 v[216:217], s[30:31], 0, v[134:135]
	s_addc_u32 s55, s31, 0
	s_add_i32 s16, s48, s33
	global_load_lds_dwordx4 v[216:217], off
	v_lshl_add_u64 v[218:219], s[54:55], 0, v[130:131]
	s_mov_b32 m0, s16
	v_lshl_add_u64 v[220:221], s[36:37], 0, v[132:133]
	global_load_lds_dwordx4 v[218:219], off
	v_lshl_add_u64 v[218:219], s[54:55], 0, v[134:135]
	s_add_i32 m0, s16, 0x2000
	s_nop 0
	global_load_lds_dwordx4 v[218:219], off
	v_lshl_add_u64 v[218:219], s[36:37], 0, v[128:129]
	s_mov_b32 m0, s39
	s_nop 0
	global_load_lds_dwordx4 v[218:219], off
	s_mov_b32 m0, s40
	s_nop 0
	global_load_lds_dwordx4 v[220:221], off
	s_waitcnt vmcnt(8)
	s_waitcnt lgkmcnt(0)
	s_barrier
	s_setprio 1
	s_waitcnt lgkmcnt(0)
	v_mfma_f32_16x16x32_bf16 v[60:63], v[144:147], v[184:187], 0
	v_mfma_f32_16x16x32_bf16 v[56:59], v[160:163], v[184:187], 0
	v_mfma_f32_16x16x32_bf16 v[52:55], v[144:147], v[192:195], 0
	v_mfma_f32_16x16x32_bf16 v[40:43], v[160:163], v[192:195], 0
	v_mfma_f32_16x16x32_bf16 v[36:39], v[144:147], v[200:203], 0
	v_mfma_f32_16x16x32_bf16 v[24:27], v[160:163], v[200:203], 0
	v_mfma_f32_16x16x32_bf16 v[20:23], v[144:147], v[208:211], 0
	v_mfma_f32_16x16x32_bf16 v[8:11], v[160:163], v[208:211], 0
	v_mfma_f32_16x16x32_bf16 v[60:63], v[156:159], v[188:191], v[60:63]
	v_mfma_f32_16x16x32_bf16 v[56:59], v[164:167], v[188:191], v[56:59]
	v_mfma_f32_16x16x32_bf16 v[52:55], v[156:159], v[196:199], v[52:55]
	v_mfma_f32_16x16x32_bf16 v[40:43], v[164:167], v[196:199], v[40:43]
	v_mfma_f32_16x16x32_bf16 v[36:39], v[156:159], v[204:207], v[36:39]
	v_mfma_f32_16x16x32_bf16 v[24:27], v[164:167], v[204:207], v[24:27]
	v_mfma_f32_16x16x32_bf16 v[20:23], v[156:159], v[212:215], v[20:23]
	v_mfma_f32_16x16x32_bf16 v[8:11], v[164:167], v[212:215], v[8:11]
	v_mfma_f32_16x16x32_bf16 v[48:51], v[168:171], v[184:187], 0
	v_mfma_f32_16x16x32_bf16 v[44:47], v[176:179], v[184:187], 0
	v_mfma_f32_16x16x32_bf16 v[32:35], v[168:171], v[192:195], 0
	v_mfma_f32_16x16x32_bf16 v[28:31], v[176:179], v[192:195], 0
	v_mfma_f32_16x16x32_bf16 v[16:19], v[168:171], v[200:203], 0
	v_mfma_f32_16x16x32_bf16 v[12:15], v[176:179], v[200:203], 0
	v_mfma_f32_16x16x32_bf16 v[4:7], v[168:171], v[208:211], 0
	v_mfma_f32_16x16x32_bf16 v[0:3], v[176:179], v[208:211], 0
	v_mfma_f32_16x16x32_bf16 v[48:51], v[172:175], v[188:191], v[48:51]
	v_mfma_f32_16x16x32_bf16 v[44:47], v[180:183], v[188:191], v[44:47]
	v_mfma_f32_16x16x32_bf16 v[32:35], v[172:175], v[196:199], v[32:35]
	v_mfma_f32_16x16x32_bf16 v[28:31], v[180:183], v[196:199], v[28:31]
	v_mfma_f32_16x16x32_bf16 v[16:19], v[172:175], v[204:207], v[16:19]
	v_mfma_f32_16x16x32_bf16 v[12:15], v[180:183], v[204:207], v[12:15]
	v_mfma_f32_16x16x32_bf16 v[4:7], v[172:175], v[212:215], v[4:7]
	v_mfma_f32_16x16x32_bf16 v[0:3], v[180:183], v[212:215], v[0:3]
	s_setprio 0
	s_barrier
	s_branch .Lpeelp7_mid
.LBB0_762:
	ds_read_b128 v[144:147], v153
	ds_read_b128 v[156:159], v153 offset:1024
	ds_read_b128 v[160:163], v153 offset:2048
	ds_read_b128 v[164:167], v153 offset:3072
	ds_read_b128 v[168:171], v154
	ds_read_b128 v[172:175], v154 offset:1024
	ds_read_b128 v[176:179], v154 offset:2048
	ds_read_b128 v[180:183], v154 offset:3072
	s_add_u32 s16, s28, 0xfff50080
	s_addc_u32 s30, s29, -1
	s_cmp_eq_u32 s53, 40
	s_cselect_b32 s37, s3, s30
	s_cselect_b32 s36, s2, s16
	s_cselect_b32 s31, s25, s52
	s_cselect_b32 s30, s24, s51
	v_lshl_add_u64 v[148:149], s[28:29], 0, v[136:137]
	s_add_i32 m0, s39, 0xc000
	ds_read_b128 v[184:187], v155
	ds_read_b128 v[188:191], v155 offset:1024
	ds_read_b128 v[192:195], v155 offset:2048
	ds_read_b128 v[196:199], v155 offset:3072
	ds_read_b128 v[200:203], v155 offset:4096
	ds_read_b128 v[204:207], v155 offset:5120
	ds_read_b128 v[208:211], v155 offset:6144
	ds_read_b128 v[212:215], v155 offset:7168
	global_load_lds_dwordx4 v[148:149], off
	v_lshl_add_u64 v[148:149], s[28:29], 0, v[138:139]
	s_add_i32 m0, s39, 0xe000
	s_nop 0
	global_load_lds_dwordx4 v[148:149], off
	s_waitcnt vmcnt(8)
	s_waitcnt lgkmcnt(0)
	s_barrier
	s_setprio 1
	s_waitcnt lgkmcnt(0)
	v_mfma_f32_16x16x32_bf16 v[124:127], v[144:147], v[184:187], v[124:127]
	v_mfma_f32_16x16x32_bf16 v[120:123], v[160:163], v[184:187], v[120:123]
	v_mfma_f32_16x16x32_bf16 v[116:119], v[144:147], v[192:195], v[116:119]
	v_mfma_f32_16x16x32_bf16 v[104:107], v[160:163], v[192:195], v[104:107]
	v_mfma_f32_16x16x32_bf16 v[100:103], v[144:147], v[200:203], v[100:103]
	v_mfma_f32_16x16x32_bf16 v[88:91], v[160:163], v[200:203], v[88:91]
	v_mfma_f32_16x16x32_bf16 v[84:87], v[144:147], v[208:211], v[84:87]
	v_mfma_f32_16x16x32_bf16 v[72:75], v[160:163], v[208:211], v[72:75]
	v_mfma_f32_16x16x32_bf16 v[124:127], v[156:159], v[188:191], v[124:127]
	v_mfma_f32_16x16x32_bf16 v[120:123], v[164:167], v[188:191], v[120:123]
	v_mfma_f32_16x16x32_bf16 v[116:119], v[156:159], v[196:199], v[116:119]
	v_mfma_f32_16x16x32_bf16 v[104:107], v[164:167], v[196:199], v[104:107]
	v_mfma_f32_16x16x32_bf16 v[100:103], v[156:159], v[204:207], v[100:103]
	v_mfma_f32_16x16x32_bf16 v[88:91], v[164:167], v[204:207], v[88:91]
	v_mfma_f32_16x16x32_bf16 v[84:87], v[156:159], v[212:215], v[84:87]
	v_mfma_f32_16x16x32_bf16 v[72:75], v[164:167], v[212:215], v[72:75]
	v_mfma_f32_16x16x32_bf16 v[112:115], v[168:171], v[184:187], v[112:115]
	v_mfma_f32_16x16x32_bf16 v[108:111], v[176:179], v[184:187], v[108:111]
	v_mfma_f32_16x16x32_bf16 v[96:99], v[168:171], v[192:195], v[96:99]
	v_mfma_f32_16x16x32_bf16 v[92:95], v[176:179], v[192:195], v[92:95]
	v_mfma_f32_16x16x32_bf16 v[80:83], v[168:171], v[200:203], v[80:83]
	v_mfma_f32_16x16x32_bf16 v[76:79], v[176:179], v[200:203], v[76:79]
	v_mfma_f32_16x16x32_bf16 v[68:71], v[168:171], v[208:211], v[68:71]
	v_mfma_f32_16x16x32_bf16 v[64:67], v[176:179], v[208:211], v[64:67]
	v_mfma_f32_16x16x32_bf16 v[112:115], v[172:175], v[188:191], v[112:115]
	v_mfma_f32_16x16x32_bf16 v[108:111], v[180:183], v[188:191], v[108:111]
	v_mfma_f32_16x16x32_bf16 v[96:99], v[172:175], v[196:199], v[96:99]
	v_mfma_f32_16x16x32_bf16 v[92:95], v[180:183], v[196:199], v[92:95]
	v_mfma_f32_16x16x32_bf16 v[80:83], v[172:175], v[204:207], v[80:83]
	v_mfma_f32_16x16x32_bf16 v[76:79], v[180:183], v[204:207], v[76:79]
	v_mfma_f32_16x16x32_bf16 v[68:71], v[172:175], v[212:215], v[68:71]
	v_mfma_f32_16x16x32_bf16 v[64:67], v[180:183], v[212:215], v[64:67]
	s_setprio 0
	s_barrier
	s_add_i32 s16, s47, s33
	v_lshl_add_u64 v[148:149], s[30:31], 0, v[130:131]
	s_mov_b32 m0, s16
	ds_read_b128 v[184:187], v155 offset:16384
	ds_read_b128 v[188:191], v155 offset:17408
	ds_read_b128 v[192:195], v155 offset:18432
	ds_read_b128 v[196:199], v155 offset:19456
	ds_read_b128 v[200:203], v155 offset:20480
	ds_read_b128 v[204:207], v155 offset:21504
	ds_read_b128 v[208:211], v155 offset:22528
	ds_read_b128 v[212:215], v155 offset:23552
	global_load_lds_dwordx4 v[148:149], off
	s_add_i32 m0, s16, 0x2000
	s_add_u32 s54, s30, 0xb0000
	v_lshl_add_u64 v[216:217], s[30:31], 0, v[134:135]
	s_addc_u32 s55, s31, 0
	s_add_i32 s16, s48, s33
	global_load_lds_dwordx4 v[216:217], off
	v_lshl_add_u64 v[218:219], s[54:55], 0, v[130:131]
	s_mov_b32 m0, s16
	v_lshl_add_u64 v[220:221], s[36:37], 0, v[132:133]
	global_load_lds_dwordx4 v[218:219], off
	v_lshl_add_u64 v[218:219], s[54:55], 0, v[134:135]
	s_add_i32 m0, s16, 0x2000
	s_nop 0
	global_load_lds_dwordx4 v[218:219], off
	v_lshl_add_u64 v[218:219], s[36:37], 0, v[128:129]
	s_mov_b32 m0, s39
	s_nop 0
	global_load_lds_dwordx4 v[218:219], off
	s_mov_b32 m0, s40
	s_nop 0
	global_load_lds_dwordx4 v[220:221], off
	s_waitcnt vmcnt(8)
	s_waitcnt lgkmcnt(0)
	s_barrier
	s_setprio 1
	s_waitcnt lgkmcnt(0)
	v_mfma_f32_16x16x32_bf16 v[60:63], v[144:147], v[184:187], v[60:63]
	v_mfma_f32_16x16x32_bf16 v[56:59], v[160:163], v[184:187], v[56:59]
	v_mfma_f32_16x16x32_bf16 v[52:55], v[144:147], v[192:195], v[52:55]
	v_mfma_f32_16x16x32_bf16 v[40:43], v[160:163], v[192:195], v[40:43]
	v_mfma_f32_16x16x32_bf16 v[36:39], v[144:147], v[200:203], v[36:39]
	v_mfma_f32_16x16x32_bf16 v[24:27], v[160:163], v[200:203], v[24:27]
	v_mfma_f32_16x16x32_bf16 v[20:23], v[144:147], v[208:211], v[20:23]
	v_mfma_f32_16x16x32_bf16 v[8:11], v[160:163], v[208:211], v[8:11]
	v_mfma_f32_16x16x32_bf16 v[60:63], v[156:159], v[188:191], v[60:63]
	v_mfma_f32_16x16x32_bf16 v[56:59], v[164:167], v[188:191], v[56:59]
	v_mfma_f32_16x16x32_bf16 v[52:55], v[156:159], v[196:199], v[52:55]
	v_mfma_f32_16x16x32_bf16 v[40:43], v[164:167], v[196:199], v[40:43]
	v_mfma_f32_16x16x32_bf16 v[36:39], v[156:159], v[204:207], v[36:39]
	v_mfma_f32_16x16x32_bf16 v[24:27], v[164:167], v[204:207], v[24:27]
	v_mfma_f32_16x16x32_bf16 v[20:23], v[156:159], v[212:215], v[20:23]
	v_mfma_f32_16x16x32_bf16 v[8:11], v[164:167], v[212:215], v[8:11]
	v_mfma_f32_16x16x32_bf16 v[48:51], v[168:171], v[184:187], v[48:51]
	v_mfma_f32_16x16x32_bf16 v[44:47], v[176:179], v[184:187], v[44:47]
	v_mfma_f32_16x16x32_bf16 v[32:35], v[168:171], v[192:195], v[32:35]
	v_mfma_f32_16x16x32_bf16 v[28:31], v[176:179], v[192:195], v[28:31]
	v_mfma_f32_16x16x32_bf16 v[16:19], v[168:171], v[200:203], v[16:19]
	v_mfma_f32_16x16x32_bf16 v[12:15], v[176:179], v[200:203], v[12:15]
	v_mfma_f32_16x16x32_bf16 v[4:7], v[168:171], v[208:211], v[4:7]
	v_mfma_f32_16x16x32_bf16 v[0:3], v[176:179], v[208:211], v[0:3]
	v_mfma_f32_16x16x32_bf16 v[48:51], v[172:175], v[188:191], v[48:51]
	v_mfma_f32_16x16x32_bf16 v[44:47], v[180:183], v[188:191], v[44:47]
	v_mfma_f32_16x16x32_bf16 v[32:35], v[172:175], v[196:199], v[32:35]
	v_mfma_f32_16x16x32_bf16 v[28:31], v[180:183], v[196:199], v[28:31]
	v_mfma_f32_16x16x32_bf16 v[16:19], v[172:175], v[204:207], v[16:19]
	v_mfma_f32_16x16x32_bf16 v[12:15], v[180:183], v[204:207], v[12:15]
	v_mfma_f32_16x16x32_bf16 v[4:7], v[172:175], v[212:215], v[4:7]
	v_mfma_f32_16x16x32_bf16 v[0:3], v[180:183], v[212:215], v[0:3]
	s_setprio 0
	s_barrier
.Lpeelp7_mid:
	s_add_i32 s16, 0, 0x18000
	s_add_i32 s54, 0, 0x1c000
	v_add_u32_e32 v164, s16, v151
	v_add_u32_e32 v180, s54, v151
	ds_read_b128 v[144:147], v164
	ds_read_b128 v[156:159], v164 offset:1024
	ds_read_b128 v[160:163], v164 offset:2048
	ds_read_b128 v[164:167], v164 offset:3072
	ds_read_b128 v[168:171], v180
	ds_read_b128 v[172:175], v180 offset:1024
	ds_read_b128 v[176:179], v180 offset:2048
	ds_read_b128 v[180:183], v180 offset:3072
	s_add_u32 s36, s36, 0xb0000
	s_addc_u32 s37, s37, 0
	s_mov_b32 m0, s41
	v_lshl_add_u64 v[222:223], s[36:37], 0, v[128:129]
	ds_read_b128 v[184:187], v155 offset:32768
	ds_read_b128 v[188:191], v155 offset:33792
	ds_read_b128 v[192:195], v155 offset:34816
	ds_read_b128 v[196:199], v155 offset:35840
	ds_read_b128 v[200:203], v155 offset:36864
	ds_read_b128 v[204:207], v155 offset:37888
	ds_read_b128 v[208:211], v155 offset:38912
	ds_read_b128 v[212:215], v155 offset:39936
	global_load_lds_dwordx4 v[222:223], off
	v_lshl_add_u64 v[222:223], s[36:37], 0, v[132:133]
	s_mov_b32 m0, s42
	s_nop 0
	global_load_lds_dwordx4 v[222:223], off
	s_waitcnt vmcnt(8)
	s_waitcnt lgkmcnt(0)
	s_barrier
	s_setprio 1
	s_waitcnt lgkmcnt(0)
	v_mfma_f32_16x16x32_bf16 v[124:127], v[144:147], v[184:187], v[124:127]
	v_mfma_f32_16x16x32_bf16 v[120:123], v[160:163], v[184:187], v[120:123]
	v_mfma_f32_16x16x32_bf16 v[116:119], v[144:147], v[192:195], v[116:119]
	v_mfma_f32_16x16x32_bf16 v[104:107], v[160:163], v[192:195], v[104:107]
	v_mfma_f32_16x16x32_bf16 v[100:103], v[144:147], v[200:203], v[100:103]
	v_mfma_f32_16x16x32_bf16 v[88:91], v[160:163], v[200:203], v[88:91]
	v_mfma_f32_16x16x32_bf16 v[84:87], v[144:147], v[208:211], v[84:87]
	v_mfma_f32_16x16x32_bf16 v[72:75], v[160:163], v[208:211], v[72:75]
	v_mfma_f32_16x16x32_bf16 v[124:127], v[156:159], v[188:191], v[124:127]
	v_mfma_f32_16x16x32_bf16 v[120:123], v[164:167], v[188:191], v[120:123]
	v_mfma_f32_16x16x32_bf16 v[116:119], v[156:159], v[196:199], v[116:119]
	v_mfma_f32_16x16x32_bf16 v[104:107], v[164:167], v[196:199], v[104:107]
	v_mfma_f32_16x16x32_bf16 v[100:103], v[156:159], v[204:207], v[100:103]
	v_mfma_f32_16x16x32_bf16 v[88:91], v[164:167], v[204:207], v[88:91]
	v_mfma_f32_16x16x32_bf16 v[84:87], v[156:159], v[212:215], v[84:87]
	v_mfma_f32_16x16x32_bf16 v[72:75], v[164:167], v[212:215], v[72:75]
	v_mfma_f32_16x16x32_bf16 v[112:115], v[168:171], v[184:187], v[112:115]
	v_mfma_f32_16x16x32_bf16 v[108:111], v[176:179], v[184:187], v[108:111]
	v_mfma_f32_16x16x32_bf16 v[96:99], v[168:171], v[192:195], v[96:99]
	v_mfma_f32_16x16x32_bf16 v[92:95], v[176:179], v[192:195], v[92:95]
	v_mfma_f32_16x16x32_bf16 v[80:83], v[168:171], v[200:203], v[80:83]
	v_mfma_f32_16x16x32_bf16 v[76:79], v[176:179], v[200:203], v[76:79]
	v_mfma_f32_16x16x32_bf16 v[68:71], v[168:171], v[208:211], v[68:71]
	v_mfma_f32_16x16x32_bf16 v[64:67], v[176:179], v[208:211], v[64:67]
	v_mfma_f32_16x16x32_bf16 v[112:115], v[172:175], v[188:191], v[112:115]
	v_mfma_f32_16x16x32_bf16 v[108:111], v[180:183], v[188:191], v[108:111]
	v_mfma_f32_16x16x32_bf16 v[96:99], v[172:175], v[196:199], v[96:99]
	v_mfma_f32_16x16x32_bf16 v[92:95], v[180:183], v[196:199], v[92:95]
	v_mfma_f32_16x16x32_bf16 v[80:83], v[172:175], v[204:207], v[80:83]
	v_mfma_f32_16x16x32_bf16 v[76:79], v[180:183], v[204:207], v[76:79]
	v_mfma_f32_16x16x32_bf16 v[68:71], v[172:175], v[212:215], v[68:71]
	v_mfma_f32_16x16x32_bf16 v[64:67], v[180:183], v[212:215], v[64:67]
	s_setprio 0
	s_barrier
	s_add_i32 s16, s16, s33
	v_lshl_add_u64 v[148:149], v[148:149], 0, s[8:9]
	s_mov_b32 m0, s16
	ds_read_b128 v[184:187], v155 offset:49152
	ds_read_b128 v[188:191], v155 offset:50176
	ds_read_b128 v[192:195], v155 offset:51200
	ds_read_b128 v[196:199], v155 offset:52224
	ds_read_b128 v[200:203], v155 offset:53248
	ds_read_b128 v[204:207], v155 offset:54272
	ds_read_b128 v[208:211], v155 offset:55296
	ds_read_b128 v[212:215], v155 offset:56320
	global_load_lds_dwordx4 v[148:149], off
	s_add_i32 m0, s16, 0x2000
	s_add_u32 s30, s30, 0xb0080
	v_lshl_add_u64 v[148:149], v[216:217], 0, s[8:9]
	s_addc_u32 s31, s31, 0
	s_add_i32 s16, s54, s33
	global_load_lds_dwordx4 v[148:149], off
	v_lshl_add_u64 v[148:149], s[30:31], 0, v[130:131]
	s_mov_b32 m0, s16
	s_nop 0
	global_load_lds_dwordx4 v[148:149], off
	v_lshl_add_u64 v[148:149], s[30:31], 0, v[134:135]
	s_add_i32 m0, s16, 0x2000
	s_nop 0
	global_load_lds_dwordx4 v[148:149], off
	v_lshl_add_u64 v[148:149], v[218:219], 0, s[8:9]
	s_mov_b32 m0, s45
	s_nop 0
	global_load_lds_dwordx4 v[148:149], off
	v_lshl_add_u64 v[148:149], v[220:221], 0, s[8:9]
	s_mov_b32 m0, s46
	s_nop 0
	global_load_lds_dwordx4 v[148:149], off
	s_waitcnt vmcnt(8)
	s_waitcnt lgkmcnt(0)
	s_barrier
	s_setprio 1
	s_waitcnt lgkmcnt(0)
	v_mfma_f32_16x16x32_bf16 v[60:63], v[144:147], v[184:187], v[60:63]
	v_mfma_f32_16x16x32_bf16 v[56:59], v[160:163], v[184:187], v[56:59]
	v_mfma_f32_16x16x32_bf16 v[52:55], v[144:147], v[192:195], v[52:55]
	v_mfma_f32_16x16x32_bf16 v[40:43], v[160:163], v[192:195], v[40:43]
	v_mfma_f32_16x16x32_bf16 v[36:39], v[144:147], v[200:203], v[36:39]
	v_mfma_f32_16x16x32_bf16 v[24:27], v[160:163], v[200:203], v[24:27]
	v_mfma_f32_16x16x32_bf16 v[20:23], v[144:147], v[208:211], v[20:23]
	v_mfma_f32_16x16x32_bf16 v[8:11], v[160:163], v[208:211], v[8:11]
	v_mfma_f32_16x16x32_bf16 v[60:63], v[156:159], v[188:191], v[60:63]
	v_mfma_f32_16x16x32_bf16 v[56:59], v[164:167], v[188:191], v[56:59]
	v_mfma_f32_16x16x32_bf16 v[52:55], v[156:159], v[196:199], v[52:55]
	v_mfma_f32_16x16x32_bf16 v[40:43], v[164:167], v[196:199], v[40:43]
	v_mfma_f32_16x16x32_bf16 v[36:39], v[156:159], v[204:207], v[36:39]
	v_mfma_f32_16x16x32_bf16 v[24:27], v[164:167], v[204:207], v[24:27]
	v_mfma_f32_16x16x32_bf16 v[20:23], v[156:159], v[212:215], v[20:23]
	v_mfma_f32_16x16x32_bf16 v[8:11], v[164:167], v[212:215], v[8:11]
	v_mfma_f32_16x16x32_bf16 v[48:51], v[168:171], v[184:187], v[48:51]
	v_mfma_f32_16x16x32_bf16 v[44:47], v[176:179], v[184:187], v[44:47]
	v_mfma_f32_16x16x32_bf16 v[32:35], v[168:171], v[192:195], v[32:35]
	v_mfma_f32_16x16x32_bf16 v[28:31], v[176:179], v[192:195], v[28:31]
	v_mfma_f32_16x16x32_bf16 v[16:19], v[168:171], v[200:203], v[16:19]
	v_mfma_f32_16x16x32_bf16 v[12:15], v[176:179], v[200:203], v[12:15]
	v_mfma_f32_16x16x32_bf16 v[4:7], v[168:171], v[208:211], v[4:7]
	v_mfma_f32_16x16x32_bf16 v[0:3], v[176:179], v[208:211], v[0:3]
	v_mfma_f32_16x16x32_bf16 v[48:51], v[172:175], v[188:191], v[48:51]
	v_mfma_f32_16x16x32_bf16 v[44:47], v[180:183], v[188:191], v[44:47]
	v_mfma_f32_16x16x32_bf16 v[32:35], v[172:175], v[196:199], v[32:35]
	v_mfma_f32_16x16x32_bf16 v[28:31], v[180:183], v[196:199], v[28:31]
	v_mfma_f32_16x16x32_bf16 v[16:19], v[172:175], v[204:207], v[16:19]
	v_mfma_f32_16x16x32_bf16 v[12:15], v[180:183], v[204:207], v[12:15]
	v_mfma_f32_16x16x32_bf16 v[4:7], v[172:175], v[212:215], v[4:7]
	v_mfma_f32_16x16x32_bf16 v[0:3], v[180:183], v[212:215], v[0:3]
	s_setprio 0
	s_barrier
	s_add_i32 s53, s53, 2
	s_add_u32 s28, s28, 0x100
	s_addc_u32 s29, s29, 0
	s_add_u32 s51, s51, 0x100
	s_addc_u32 s52, s52, 0
	s_cmp_gt_u32 s53, 41
	s_cbranch_scc0 .LBB0_762
	s_and_b64 vcc, exec, s[10:11]
	s_cbranch_vccz .LBB0_765
	s_barrier
